# peeled first K-loop iteration in all six GEMM phases: first MFMA of each accumulator takes C=0, the 128 per-unit zero-init v_movs are deleted
# speedup vs baseline: 1.0161x; 1.0161x over previous
.LBB0_213:
	s_ashr_i32 s77, s76, 31
	s_lshl_b64 s[34:35], s[76:77], 18
	s_add_u32 s78, s22, s34
	s_addc_u32 s79, s23, s35
	s_and_b64 s[34:35], s[2:3], exec
	s_cselect_b32 s34, s79, s87
	s_cselect_b32 s35, s78, s86
	s_ashr_i32 s75, s74, 31
	s_lshl_b64 s[80:81], s[74:75], 18
	s_add_u32 s80, s46, s80
	s_addc_u32 s81, s47, s81
	s_and_b64 s[90:91], s[2:3], exec
	s_cselect_b32 s75, s81, s85
	s_cselect_b32 s77, s80, s84
	s_add_u32 s89, s84, 0x100
	.p2align 8
	s_addc_u32 s90, s85, 0
	s_add_u32 s84, s86, 0x20080
	s_addc_u32 s85, s87, 0
	s_mov_b32 s86, -2
.Lpeel_214:
	ds_read_b128 v[66:69], v161
	ds_read_b128 v[70:73], v161 offset:1024
	ds_read_b128 v[74:77], v161 offset:2048
	ds_read_b128 v[78:81], v161 offset:3072
	ds_read_b128 v[168:171], v163
	ds_read_b128 v[172:175], v163 offset:1024
	ds_read_b128 v[176:179], v163 offset:2048
	ds_read_b128 v[180:183], v163 offset:3072
	s_add_u32 s87, s84, 0xfffe0080
	s_addc_u32 s91, s85, -1
	s_cmp_eq_u32 s86, 4
	s_cselect_b32 s95, s34, s91
	s_cselect_b32 s94, s35, s87
	s_cselect_b32 s97, s75, s90
	s_cselect_b32 s96, s77, s89
	v_lshl_add_u64 v[158:159], s[84:85], 0, v[152:153]
	s_add_i32 m0, s56, 0xc000
	ds_read_b128 v[184:187], v165
	ds_read_b128 v[188:191], v165 offset:1024
	ds_read_b128 v[192:195], v165 offset:2048
	ds_read_b128 v[196:199], v165 offset:3072
	ds_read_b128 v[200:203], v165 offset:4096
	ds_read_b128 v[204:207], v165 offset:5120
	ds_read_b128 v[208:211], v165 offset:6144
	ds_read_b128 v[212:215], v165 offset:7168
	global_load_lds_dwordx4 v[158:159], off
	v_lshl_add_u64 v[158:159], v[158:159], 0, s[4:5]
	s_add_i32 m0, s56, 0xe000
	s_nop 0
	global_load_lds_dwordx4 v[158:159], off
	s_waitcnt vmcnt(8)
	s_waitcnt lgkmcnt(0)
	s_barrier
	s_setprio 1
	s_waitcnt lgkmcnt(0)
	v_mfma_i32_16x16x64_i8 v[142:145], v[66:69], v[184:187], 0
	v_mfma_i32_16x16x64_i8 v[138:141], v[74:77], v[184:187], 0
	v_mfma_i32_16x16x64_i8 v[126:129], v[66:69], v[192:195], 0
	v_mfma_i32_16x16x64_i8 v[122:125], v[74:77], v[192:195], 0
	v_mfma_i32_16x16x64_i8 v[110:113], v[66:69], v[200:203], 0
	v_mfma_i32_16x16x64_i8 v[106:109], v[74:77], v[200:203], 0
	v_mfma_i32_16x16x64_i8 v[94:97], v[66:69], v[208:211], 0
	v_mfma_i32_16x16x64_i8 v[90:93], v[74:77], v[208:211], 0
	v_mfma_i32_16x16x64_i8 v[142:145], v[70:73], v[188:191], v[142:145]
	v_mfma_i32_16x16x64_i8 v[138:141], v[78:81], v[188:191], v[138:141]
	v_mfma_i32_16x16x64_i8 v[126:129], v[70:73], v[196:199], v[126:129]
	v_mfma_i32_16x16x64_i8 v[122:125], v[78:81], v[196:199], v[122:125]
	v_mfma_i32_16x16x64_i8 v[110:113], v[70:73], v[204:207], v[110:113]
	v_mfma_i32_16x16x64_i8 v[106:109], v[78:81], v[204:207], v[106:109]
	v_mfma_i32_16x16x64_i8 v[94:97], v[70:73], v[212:215], v[94:97]
	v_mfma_i32_16x16x64_i8 v[90:93], v[78:81], v[212:215], v[90:93]
	s_setprio 0
	s_setprio 1
	v_mfma_i32_16x16x64_i8 v[134:137], v[168:171], v[184:187], 0
	v_mfma_i32_16x16x64_i8 v[130:133], v[176:179], v[184:187], 0
	v_mfma_i32_16x16x64_i8 v[118:121], v[168:171], v[192:195], 0
	v_mfma_i32_16x16x64_i8 v[114:117], v[176:179], v[192:195], 0
	v_mfma_i32_16x16x64_i8 v[102:105], v[168:171], v[200:203], 0
	v_mfma_i32_16x16x64_i8 v[98:101], v[176:179], v[200:203], 0
	v_mfma_i32_16x16x64_i8 v[86:89], v[168:171], v[208:211], 0
	v_mfma_i32_16x16x64_i8 v[82:85], v[176:179], v[208:211], 0
	v_mfma_i32_16x16x64_i8 v[134:137], v[172:175], v[188:191], v[134:137]
	v_mfma_i32_16x16x64_i8 v[130:133], v[180:183], v[188:191], v[130:133]
	v_mfma_i32_16x16x64_i8 v[118:121], v[172:175], v[196:199], v[118:121]
	v_mfma_i32_16x16x64_i8 v[114:117], v[180:183], v[196:199], v[114:117]
	v_mfma_i32_16x16x64_i8 v[102:105], v[172:175], v[204:207], v[102:105]
	v_mfma_i32_16x16x64_i8 v[98:101], v[180:183], v[204:207], v[98:101]
	v_mfma_i32_16x16x64_i8 v[86:89], v[172:175], v[212:215], v[86:89]
	v_mfma_i32_16x16x64_i8 v[82:85], v[180:183], v[212:215], v[82:85]
	s_setprio 0
	s_barrier
	s_add_i32 s87, s64, s16
	v_lshl_add_u64 v[158:159], s[96:97], 0, v[148:149]
	s_mov_b32 m0, s87
	ds_read_b128 v[184:187], v165 offset:16384
	ds_read_b128 v[188:191], v165 offset:17408
	ds_read_b128 v[192:195], v165 offset:18432
	ds_read_b128 v[196:199], v165 offset:19456
	ds_read_b128 v[200:203], v165 offset:20480
	ds_read_b128 v[204:207], v165 offset:21504
	ds_read_b128 v[208:211], v165 offset:22528
	ds_read_b128 v[212:215], v165 offset:23552
	global_load_lds_dwordx4 v[158:159], off
	v_lshl_add_u64 v[216:217], v[158:159], 0, s[4:5]
	s_add_i32 m0, s87, 0x2000
	s_add_i32 s87, s65, s16
	global_load_lds_dwordx4 v[216:217], off
	v_lshl_add_u64 v[216:217], v[158:159], 0, s[10:11]
	s_mov_b32 m0, s87
	s_nop 0
	global_load_lds_dwordx4 v[216:217], off
	v_lshl_add_u64 v[216:217], v[158:159], 0, s[12:13]
	s_add_i32 m0, s87, 0x2000
	s_nop 0
	global_load_lds_dwordx4 v[216:217], off
	v_lshl_add_u64 v[216:217], s[94:95], 0, v[146:147]
	s_mov_b32 m0, s56
	v_lshl_add_u64 v[218:219], v[216:217], 0, s[4:5]
	global_load_lds_dwordx4 v[216:217], off
	s_mov_b32 m0, s57
	s_nop 0
	global_load_lds_dwordx4 v[218:219], off
	s_waitcnt vmcnt(8)
	s_waitcnt lgkmcnt(0)
	s_barrier
	s_setprio 1
	s_waitcnt lgkmcnt(0)
	v_mfma_i32_16x16x64_i8 v[62:65], v[66:69], v[184:187], 0
	v_mfma_i32_16x16x64_i8 v[58:61], v[74:77], v[184:187], 0
	v_mfma_i32_16x16x64_i8 v[46:49], v[66:69], v[192:195], 0
	v_mfma_i32_16x16x64_i8 v[42:45], v[74:77], v[192:195], 0
	v_mfma_i32_16x16x64_i8 v[30:33], v[66:69], v[200:203], 0
	v_mfma_i32_16x16x64_i8 v[26:29], v[74:77], v[200:203], 0
	v_mfma_i32_16x16x64_i8 v[14:17], v[66:69], v[208:211], 0
	v_mfma_i32_16x16x64_i8 v[10:13], v[74:77], v[208:211], 0
	v_mfma_i32_16x16x64_i8 v[62:65], v[70:73], v[188:191], v[62:65]
	v_mfma_i32_16x16x64_i8 v[58:61], v[78:81], v[188:191], v[58:61]
	v_mfma_i32_16x16x64_i8 v[46:49], v[70:73], v[196:199], v[46:49]
	v_mfma_i32_16x16x64_i8 v[42:45], v[78:81], v[196:199], v[42:45]
	v_mfma_i32_16x16x64_i8 v[30:33], v[70:73], v[204:207], v[30:33]
	v_mfma_i32_16x16x64_i8 v[26:29], v[78:81], v[204:207], v[26:29]
	v_mfma_i32_16x16x64_i8 v[14:17], v[70:73], v[212:215], v[14:17]
	v_mfma_i32_16x16x64_i8 v[10:13], v[78:81], v[212:215], v[10:13]
	s_setprio 0
	s_setprio 1
	v_mfma_i32_16x16x64_i8 v[54:57], v[168:171], v[184:187], 0
	v_mfma_i32_16x16x64_i8 v[50:53], v[176:179], v[184:187], 0
	v_mfma_i32_16x16x64_i8 v[38:41], v[168:171], v[192:195], 0
	v_mfma_i32_16x16x64_i8 v[34:37], v[176:179], v[192:195], 0
	v_mfma_i32_16x16x64_i8 v[22:25], v[168:171], v[200:203], 0
	v_mfma_i32_16x16x64_i8 v[18:21], v[176:179], v[200:203], 0
	v_mfma_i32_16x16x64_i8 v[6:9], v[168:171], v[208:211], 0
	v_mfma_i32_16x16x64_i8 v[2:5], v[176:179], v[208:211], 0
	v_mfma_i32_16x16x64_i8 v[54:57], v[172:175], v[188:191], v[54:57]
	v_mfma_i32_16x16x64_i8 v[50:53], v[180:183], v[188:191], v[50:53]
	v_mfma_i32_16x16x64_i8 v[38:41], v[172:175], v[196:199], v[38:41]
	v_mfma_i32_16x16x64_i8 v[34:37], v[180:183], v[196:199], v[34:37]
	v_mfma_i32_16x16x64_i8 v[22:25], v[172:175], v[204:207], v[22:25]
	v_mfma_i32_16x16x64_i8 v[18:21], v[180:183], v[204:207], v[18:21]
	v_mfma_i32_16x16x64_i8 v[6:9], v[172:175], v[212:215], v[6:9]
	v_mfma_i32_16x16x64_i8 v[2:5], v[180:183], v[212:215], v[2:5]
	s_setprio 0
	s_barrier
	s_add_i32 s87, 0, 0x18000
	s_add_i32 s91, 0, 0x1c000
	v_add_u32_e32 v78, s87, v1
	v_add_u32_e32 v150, s91, v1
	ds_read_b128 v[66:69], v78
	ds_read_b128 v[70:73], v78 offset:1024
	ds_read_b128 v[74:77], v78 offset:2048
	ds_read_b128 v[78:81], v78 offset:3072
	ds_read_b128 v[168:171], v150
	ds_read_b128 v[172:175], v150 offset:1024
	ds_read_b128 v[176:179], v150 offset:2048
	ds_read_b128 v[180:183], v150 offset:3072
	s_mov_b32 m0, s58
	v_lshl_add_u64 v[218:219], v[216:217], 0, s[10:11]
	ds_read_b128 v[184:187], v165 offset:32768
	ds_read_b128 v[188:191], v165 offset:33792
	ds_read_b128 v[192:195], v165 offset:34816
	ds_read_b128 v[196:199], v165 offset:35840
	ds_read_b128 v[200:203], v165 offset:36864
	ds_read_b128 v[204:207], v165 offset:37888
	ds_read_b128 v[208:211], v165 offset:38912
	ds_read_b128 v[212:215], v165 offset:39936
	global_load_lds_dwordx4 v[218:219], off
	v_lshl_add_u64 v[218:219], v[216:217], 0, s[12:13]
	s_mov_b32 m0, s59
	s_nop 0
	global_load_lds_dwordx4 v[218:219], off
	s_waitcnt vmcnt(8)
	s_waitcnt lgkmcnt(0)
	s_barrier
	s_setprio 1
	s_waitcnt lgkmcnt(0)
	v_mfma_i32_16x16x64_i8 v[142:145], v[66:69], v[184:187], v[142:145]
	v_mfma_i32_16x16x64_i8 v[138:141], v[74:77], v[184:187], v[138:141]
	v_mfma_i32_16x16x64_i8 v[126:129], v[66:69], v[192:195], v[126:129]
	v_mfma_i32_16x16x64_i8 v[122:125], v[74:77], v[192:195], v[122:125]
	v_mfma_i32_16x16x64_i8 v[110:113], v[66:69], v[200:203], v[110:113]
	v_mfma_i32_16x16x64_i8 v[106:109], v[74:77], v[200:203], v[106:109]
	v_mfma_i32_16x16x64_i8 v[94:97], v[66:69], v[208:211], v[94:97]
	v_mfma_i32_16x16x64_i8 v[90:93], v[74:77], v[208:211], v[90:93]
	v_mfma_i32_16x16x64_i8 v[142:145], v[70:73], v[188:191], v[142:145]
	v_mfma_i32_16x16x64_i8 v[138:141], v[78:81], v[188:191], v[138:141]
	v_mfma_i32_16x16x64_i8 v[126:129], v[70:73], v[196:199], v[126:129]
	v_mfma_i32_16x16x64_i8 v[122:125], v[78:81], v[196:199], v[122:125]
	v_mfma_i32_16x16x64_i8 v[110:113], v[70:73], v[204:207], v[110:113]
	v_mfma_i32_16x16x64_i8 v[106:109], v[78:81], v[204:207], v[106:109]
	v_mfma_i32_16x16x64_i8 v[94:97], v[70:73], v[212:215], v[94:97]
	v_mfma_i32_16x16x64_i8 v[90:93], v[78:81], v[212:215], v[90:93]
	s_setprio 0
	s_setprio 1
	v_mfma_i32_16x16x64_i8 v[134:137], v[168:171], v[184:187], v[134:137]
	v_mfma_i32_16x16x64_i8 v[130:133], v[176:179], v[184:187], v[130:133]
	v_mfma_i32_16x16x64_i8 v[118:121], v[168:171], v[192:195], v[118:121]
	v_mfma_i32_16x16x64_i8 v[114:117], v[176:179], v[192:195], v[114:117]
	v_mfma_i32_16x16x64_i8 v[102:105], v[168:171], v[200:203], v[102:105]
	v_mfma_i32_16x16x64_i8 v[98:101], v[176:179], v[200:203], v[98:101]
	v_mfma_i32_16x16x64_i8 v[86:89], v[168:171], v[208:211], v[86:89]
	v_mfma_i32_16x16x64_i8 v[82:85], v[176:179], v[208:211], v[82:85]
	v_mfma_i32_16x16x64_i8 v[134:137], v[172:175], v[188:191], v[134:137]
	v_mfma_i32_16x16x64_i8 v[130:133], v[180:183], v[188:191], v[130:133]
	v_mfma_i32_16x16x64_i8 v[118:121], v[172:175], v[196:199], v[118:121]
	v_mfma_i32_16x16x64_i8 v[114:117], v[180:183], v[196:199], v[114:117]
	v_mfma_i32_16x16x64_i8 v[102:105], v[172:175], v[204:207], v[102:105]
	v_mfma_i32_16x16x64_i8 v[98:101], v[180:183], v[204:207], v[98:101]
	v_mfma_i32_16x16x64_i8 v[86:89], v[172:175], v[212:215], v[86:89]
	v_mfma_i32_16x16x64_i8 v[82:85], v[180:183], v[212:215], v[82:85]
	s_setprio 0
	s_barrier
	s_add_i32 s87, s87, s16
	v_lshl_add_u64 v[218:219], v[158:159], 0, s[48:49]
	s_mov_b32 m0, s87
	ds_read_b128 v[184:187], v165 offset:49152
	ds_read_b128 v[188:191], v165 offset:50176
	ds_read_b128 v[192:195], v165 offset:51200
	ds_read_b128 v[196:199], v165 offset:52224
	ds_read_b128 v[200:203], v165 offset:53248
	ds_read_b128 v[204:207], v165 offset:54272
	ds_read_b128 v[208:211], v165 offset:55296
	ds_read_b128 v[212:215], v165 offset:56320
	global_load_lds_dwordx4 v[218:219], off
	v_lshl_add_u64 v[218:219], v[158:159], 0, s[50:51]
	s_add_i32 m0, s87, 0x2000
	s_add_i32 s87, s91, s16
	global_load_lds_dwordx4 v[218:219], off
	v_lshl_add_u64 v[218:219], v[158:159], 0, s[52:53]
	s_mov_b32 m0, s87
	v_lshl_add_u64 v[158:159], v[158:159], 0, s[66:67]
	global_load_lds_dwordx4 v[218:219], off
	s_add_i32 m0, s87, 0x2000
	s_nop 0
	global_load_lds_dwordx4 v[158:159], off
	v_lshl_add_u64 v[158:159], v[216:217], 0, s[48:49]
	s_mov_b32 m0, s62
	s_nop 0
	global_load_lds_dwordx4 v[158:159], off
	v_lshl_add_u64 v[158:159], v[216:217], 0, s[50:51]
	s_mov_b32 m0, s63
	s_nop 0
	global_load_lds_dwordx4 v[158:159], off
	s_waitcnt vmcnt(8)
	s_waitcnt lgkmcnt(0)
	s_barrier
	s_setprio 1
	s_waitcnt lgkmcnt(0)
	v_mfma_i32_16x16x64_i8 v[62:65], v[66:69], v[184:187], v[62:65]
	v_mfma_i32_16x16x64_i8 v[58:61], v[74:77], v[184:187], v[58:61]
	v_mfma_i32_16x16x64_i8 v[46:49], v[66:69], v[192:195], v[46:49]
	v_mfma_i32_16x16x64_i8 v[42:45], v[74:77], v[192:195], v[42:45]
	v_mfma_i32_16x16x64_i8 v[30:33], v[66:69], v[200:203], v[30:33]
	v_mfma_i32_16x16x64_i8 v[26:29], v[74:77], v[200:203], v[26:29]
	v_mfma_i32_16x16x64_i8 v[14:17], v[66:69], v[208:211], v[14:17]
	v_mfma_i32_16x16x64_i8 v[10:13], v[74:77], v[208:211], v[10:13]
	v_mfma_i32_16x16x64_i8 v[62:65], v[70:73], v[188:191], v[62:65]
	v_mfma_i32_16x16x64_i8 v[58:61], v[78:81], v[188:191], v[58:61]
	v_mfma_i32_16x16x64_i8 v[46:49], v[70:73], v[196:199], v[46:49]
	v_mfma_i32_16x16x64_i8 v[42:45], v[78:81], v[196:199], v[42:45]
	v_mfma_i32_16x16x64_i8 v[30:33], v[70:73], v[204:207], v[30:33]
	v_mfma_i32_16x16x64_i8 v[26:29], v[78:81], v[204:207], v[26:29]
	v_mfma_i32_16x16x64_i8 v[14:17], v[70:73], v[212:215], v[14:17]
	v_mfma_i32_16x16x64_i8 v[10:13], v[78:81], v[212:215], v[10:13]
	s_setprio 0
	s_setprio 1
	v_mfma_i32_16x16x64_i8 v[54:57], v[168:171], v[184:187], v[54:57]
	v_mfma_i32_16x16x64_i8 v[50:53], v[176:179], v[184:187], v[50:53]
	v_mfma_i32_16x16x64_i8 v[38:41], v[168:171], v[192:195], v[38:41]
	v_mfma_i32_16x16x64_i8 v[34:37], v[176:179], v[192:195], v[34:37]
	v_mfma_i32_16x16x64_i8 v[22:25], v[168:171], v[200:203], v[22:25]
	v_mfma_i32_16x16x64_i8 v[18:21], v[176:179], v[200:203], v[18:21]
	v_mfma_i32_16x16x64_i8 v[6:9], v[168:171], v[208:211], v[6:9]
	v_mfma_i32_16x16x64_i8 v[2:5], v[176:179], v[208:211], v[2:5]
	v_mfma_i32_16x16x64_i8 v[54:57], v[172:175], v[188:191], v[54:57]
	v_mfma_i32_16x16x64_i8 v[50:53], v[180:183], v[188:191], v[50:53]
	v_mfma_i32_16x16x64_i8 v[38:41], v[172:175], v[196:199], v[38:41]
	v_mfma_i32_16x16x64_i8 v[34:37], v[180:183], v[196:199], v[34:37]
	v_mfma_i32_16x16x64_i8 v[22:25], v[172:175], v[204:207], v[22:25]
	v_mfma_i32_16x16x64_i8 v[18:21], v[180:183], v[204:207], v[18:21]
	v_mfma_i32_16x16x64_i8 v[6:9], v[172:175], v[212:215], v[6:9]
	v_mfma_i32_16x16x64_i8 v[2:5], v[180:183], v[212:215], v[2:5]
	s_setprio 0
	s_barrier
	s_add_i32 s86, s86, 2
	s_add_u32 s89, s89, 0x100
	s_addc_u32 s90, s90, 0
	s_add_u32 s84, s84, 0x100
	s_addc_u32 s85, s85, 0
	s_cmp_gt_u32 s86, 5
	s_cbranch_scc1 .Lpeel_exit_214

.Lpeel_exit_214:
	s_and_b64 vcc, exec, s[70:71]
	s_cbranch_vccz .LBB0_217
	s_barrier

.LBB0_274:
	s_add_u32 s86, s78, 0x100
	.p2align 8
	s_addc_u32 s87, s79, 0
	s_add_u32 s0, s80, 0x58080
	s_addc_u32 s1, s81, 0
	s_mov_b32 s88, -2
	s_waitcnt lgkmcnt(0)
.Lpeel_275:
	ds_read_b128 v[140:143], v186
	ds_read_b128 v[144:147], v186 offset:1024
	ds_read_b128 v[148:151], v186 offset:2048
	ds_read_b128 v[152:155], v186 offset:3072
	ds_read_b128 v[156:159], v187
	ds_read_b128 v[160:163], v187 offset:1024
	ds_read_b128 v[164:167], v187 offset:2048
	ds_read_b128 v[168:171], v187 offset:3072
	s_add_u32 s78, s0, 0xfffa8080
	s_addc_u32 s79, s1, -1
	s_cmp_eq_u32 s88, 18
	s_cselect_b32 s79, s75, s79
	s_cselect_b32 s78, s74, s78
	s_cselect_b32 s81, s77, s87
	s_cselect_b32 s80, s76, s86
	v_lshl_add_u64 v[180:181], s[0:1], 0, v[134:135]
	s_add_i32 m0, s17, 0xc000
	ds_read_b128 v[172:175], v188
	ds_read_b128 v[176:179], v188 offset:1024
	ds_read_b128 v[192:195], v188 offset:2048
	ds_read_b128 v[196:199], v188 offset:3072
	ds_read_b128 v[200:203], v188 offset:4096
	ds_read_b128 v[204:207], v188 offset:5120
	ds_read_b128 v[208:211], v188 offset:6144
	ds_read_b128 v[212:215], v188 offset:7168
	global_load_lds_dwordx4 v[180:181], off
	v_lshl_add_u64 v[180:181], v[180:181], 0, s[10:11]
	s_add_i32 m0, s17, 0xe000
	s_nop 0
	global_load_lds_dwordx4 v[180:181], off
	s_waitcnt vmcnt(8)
	s_waitcnt lgkmcnt(0)
	s_barrier
	s_setprio 1
	s_waitcnt lgkmcnt(0)
	v_mfma_scale_f32_16x16x128_f8f6f4 v[126:129], v[140:147], v[172:179], 0, v189, v189 op_sel_hi:[0, 0, 0]
	v_mfma_scale_f32_16x16x128_f8f6f4 v[122:125], v[148:155], v[172:179], 0, v189, v189 op_sel_hi:[0, 0, 0]
	v_mfma_scale_f32_16x16x128_f8f6f4 v[118:121], v[140:147], v[192:199], 0, v189, v189 op_sel_hi:[0, 0, 0]
	v_mfma_scale_f32_16x16x128_f8f6f4 v[114:117], v[148:155], v[192:199], 0, v189, v189 op_sel_hi:[0, 0, 0]
	v_mfma_scale_f32_16x16x128_f8f6f4 v[110:113], v[140:147], v[200:207], 0, v189, v189 op_sel_hi:[0, 0, 0]
	v_mfma_scale_f32_16x16x128_f8f6f4 v[106:109], v[148:155], v[200:207], 0, v189, v189 op_sel_hi:[0, 0, 0]
	v_mfma_scale_f32_16x16x128_f8f6f4 v[102:105], v[140:147], v[208:215], 0, v189, v189 op_sel_hi:[0, 0, 0]
	v_mfma_scale_f32_16x16x128_f8f6f4 v[98:101], v[148:155], v[208:215], 0, v189, v189 op_sel_hi:[0, 0, 0]
	s_setprio 0
	s_setprio 1
	v_mfma_scale_f32_16x16x128_f8f6f4 v[180:183], v[156:163], v[172:179], 0, v189, v189 op_sel_hi:[0, 0, 0]
	v_mfma_scale_f32_16x16x128_f8f6f4 v[172:175], v[164:171], v[172:179], 0, v189, v189 op_sel_hi:[0, 0, 0]
	v_mfma_scale_f32_16x16x128_f8f6f4 v[176:179], v[156:163], v[192:199], 0, v189, v189 op_sel_hi:[0, 0, 0]
	v_mfma_scale_f32_16x16x128_f8f6f4 v[192:195], v[164:171], v[192:199], 0, v189, v189 op_sel_hi:[0, 0, 0]
	v_mfma_scale_f32_16x16x128_f8f6f4 v[196:199], v[156:163], v[200:207], 0, v189, v189 op_sel_hi:[0, 0, 0]
	v_mfma_scale_f32_16x16x128_f8f6f4 v[200:203], v[164:171], v[200:207], 0, v189, v189 op_sel_hi:[0, 0, 0]
	v_mfma_scale_f32_16x16x128_f8f6f4 v[204:207], v[156:163], v[208:215], 0, v189, v189 op_sel_hi:[0, 0, 0]
	v_mfma_scale_f32_16x16x128_f8f6f4 v[208:211], v[164:171], v[208:215], 0, v189, v189 op_sel_hi:[0, 0, 0]
	s_setprio 0
	s_barrier
	v_lshl_add_u64 v[184:185], s[80:81], 0, v[132:133]
	s_add_i32 s80, s82, s16
	s_mov_b32 m0, s80
	s_nop 1
	ds_read_b128 v[34:37], v188 offset:16384
	ds_read_b128 v[38:41], v188 offset:17408
	ds_read_b128 v[42:45], v188 offset:18432
	ds_read_b128 v[46:49], v188 offset:19456
	ds_read_b128 v[50:53], v188 offset:20480
	ds_read_b128 v[54:57], v188 offset:21504
	ds_read_b128 v[58:61], v188 offset:22528
	ds_read_b128 v[62:65], v188 offset:23552
	global_load_lds_dwordx4 v[184:185], off
	v_lshl_add_u64 v[212:213], v[184:185], 0, s[10:11]
	s_add_i32 m0, s80, 0x2000
	s_add_i32 s80, s83, s16
	global_load_lds_dwordx4 v[212:213], off
	v_lshl_add_u64 v[212:213], v[184:185], 0, s[12:13]
	s_mov_b32 m0, s80
	v_lshl_add_u64 v[252:253], s[78:79], 0, v[130:131]
	global_load_lds_dwordx4 v[212:213], off
	v_lshl_add_u64 v[212:213], v[184:185], 0, s[14:15]
	s_add_i32 m0, s80, 0x2000
	s_nop 0
	global_load_lds_dwordx4 v[212:213], off
	s_mov_b32 m0, s17
	v_lshl_add_u64 v[212:213], v[252:253], 0, s[10:11]
	global_load_lds_dwordx4 v[252:253], off
	s_mov_b32 m0, s33
	s_nop 0
	global_load_lds_dwordx4 v[212:213], off
	s_waitcnt vmcnt(8)
	s_waitcnt lgkmcnt(0)
	s_barrier
	s_setprio 1
	s_waitcnt lgkmcnt(0)
	v_mfma_scale_f32_16x16x128_f8f6f4 v[94:97], v[140:147], v[34:41], 0, v189, v189 op_sel_hi:[0, 0, 0]
	v_mfma_scale_f32_16x16x128_f8f6f4 v[90:93], v[148:155], v[34:41], 0, v189, v189 op_sel_hi:[0, 0, 0]
	v_mfma_scale_f32_16x16x128_f8f6f4 v[86:89], v[140:147], v[42:49], 0, v189, v189 op_sel_hi:[0, 0, 0]
	v_mfma_scale_f32_16x16x128_f8f6f4 v[82:85], v[148:155], v[42:49], 0, v189, v189 op_sel_hi:[0, 0, 0]
	v_mfma_scale_f32_16x16x128_f8f6f4 v[78:81], v[140:147], v[50:57], 0, v189, v189 op_sel_hi:[0, 0, 0]
	v_mfma_scale_f32_16x16x128_f8f6f4 v[74:77], v[148:155], v[50:57], 0, v189, v189 op_sel_hi:[0, 0, 0]
	v_mfma_scale_f32_16x16x128_f8f6f4 v[212:215], v[140:147], v[58:65], 0, v189, v189 op_sel_hi:[0, 0, 0]
	v_mfma_scale_f32_16x16x128_f8f6f4 v[216:219], v[148:155], v[58:65], 0, v189, v189 op_sel_hi:[0, 0, 0]
	s_setprio 0
	s_setprio 1
	v_mfma_scale_f32_16x16x128_f8f6f4 v[220:223], v[156:163], v[34:41], 0, v189, v189 op_sel_hi:[0, 0, 0]
	v_mfma_scale_f32_16x16x128_f8f6f4 v[224:227], v[164:171], v[34:41], 0, v189, v189 op_sel_hi:[0, 0, 0]
	v_mfma_scale_f32_16x16x128_f8f6f4 v[228:231], v[156:163], v[42:49], 0, v189, v189 op_sel_hi:[0, 0, 0]
	v_mfma_scale_f32_16x16x128_f8f6f4 v[232:235], v[164:171], v[42:49], 0, v189, v189 op_sel_hi:[0, 0, 0]
	v_mfma_scale_f32_16x16x128_f8f6f4 v[236:239], v[156:163], v[50:57], 0, v189, v189 op_sel_hi:[0, 0, 0]
	v_mfma_scale_f32_16x16x128_f8f6f4 v[240:243], v[164:171], v[50:57], 0, v189, v189 op_sel_hi:[0, 0, 0]
	v_mfma_scale_f32_16x16x128_f8f6f4 v[244:247], v[156:163], v[58:65], 0, v189, v189 op_sel_hi:[0, 0, 0]
	v_mfma_scale_f32_16x16x128_f8f6f4 v[248:251], v[164:171], v[58:65], 0, v189, v189 op_sel_hi:[0, 0, 0]
	s_setprio 0
	s_barrier
	s_add_i32 s78, 0, 0x18000
	s_add_i32 s79, 0, 0x1c000
	v_add_u32_e32 v14, s78, v1
	v_add_u32_e32 v18, s79, v1
	s_nop 0
	ds_read_b128 v[2:5], v14
	ds_read_b128 v[6:9], v14 offset:1024
	ds_read_b128 v[10:13], v14 offset:2048
	ds_read_b128 v[14:17], v14 offset:3072
	ds_read_b128 v[140:143], v18
	ds_read_b128 v[144:147], v18 offset:1024
	ds_read_b128 v[148:151], v18 offset:2048
	ds_read_b128 v[152:155], v18 offset:3072
	s_mov_b32 m0, s54
	v_lshl_add_u64 v[42:43], v[252:253], 0, s[12:13]
	ds_read_b128 v[18:21], v188 offset:32768
	ds_read_b128 v[22:25], v188 offset:33792
	ds_read_b128 v[26:29], v188 offset:34816
	ds_read_b128 v[30:33], v188 offset:35840
	ds_read_b128 v[34:37], v188 offset:36864
	ds_read_b128 v[38:41], v188 offset:37888
	ds_read_b128 v[66:69], v188 offset:38912
	ds_read_b128 v[70:73], v188 offset:39936
	global_load_lds_dwordx4 v[42:43], off
	v_lshl_add_u64 v[42:43], v[252:253], 0, s[14:15]
	s_mov_b32 m0, s55
	s_nop 0
	global_load_lds_dwordx4 v[42:43], off
	s_waitcnt vmcnt(8)
	s_waitcnt lgkmcnt(0)
	s_barrier
	s_setprio 1
	s_waitcnt lgkmcnt(0)
	v_mfma_scale_f32_16x16x128_f8f6f4 v[126:129], v[2:9], v[18:25], v[126:129], v189, v189 op_sel_hi:[0,0,0]
	v_mfma_scale_f32_16x16x128_f8f6f4 v[122:125], v[10:17], v[18:25], v[122:125], v189, v189 op_sel_hi:[0,0,0]
	v_mfma_scale_f32_16x16x128_f8f6f4 v[118:121], v[2:9], v[26:33], v[118:121], v189, v189 op_sel_hi:[0,0,0]
	v_mfma_scale_f32_16x16x128_f8f6f4 v[114:117], v[10:17], v[26:33], v[114:117], v189, v189 op_sel_hi:[0,0,0]
	v_mfma_scale_f32_16x16x128_f8f6f4 v[110:113], v[2:9], v[34:41], v[110:113], v189, v189 op_sel_hi:[0,0,0]
	v_mfma_scale_f32_16x16x128_f8f6f4 v[106:109], v[10:17], v[34:41], v[106:109], v189, v189 op_sel_hi:[0,0,0]
	v_mfma_scale_f32_16x16x128_f8f6f4 v[102:105], v[2:9], v[66:73], v[102:105], v189, v189 op_sel_hi:[0,0,0]
	v_mfma_scale_f32_16x16x128_f8f6f4 v[98:101], v[10:17], v[66:73], v[98:101], v189, v189 op_sel_hi:[0,0,0]
	s_setprio 0
	s_setprio 1
	v_mfma_scale_f32_16x16x128_f8f6f4 v[62:65], v[140:147], v[18:25], v[180:183], v189, v189 op_sel_hi:[0,0,0]
	v_mfma_scale_f32_16x16x128_f8f6f4 v[58:61], v[148:155], v[18:25], v[172:175], v189, v189 op_sel_hi:[0,0,0]
	v_mfma_scale_f32_16x16x128_f8f6f4 v[54:57], v[140:147], v[26:33], v[176:179], v189, v189 op_sel_hi:[0,0,0]
	v_mfma_scale_f32_16x16x128_f8f6f4 v[50:53], v[148:155], v[26:33], v[192:195], v189, v189 op_sel_hi:[0,0,0]
	v_mfma_scale_f32_16x16x128_f8f6f4 v[46:49], v[140:147], v[34:41], v[196:199], v189, v189 op_sel_hi:[0,0,0]
	v_mfma_scale_f32_16x16x128_f8f6f4 v[42:45], v[148:155], v[34:41], v[200:203], v189, v189 op_sel_hi:[0,0,0]
	v_mfma_scale_f32_16x16x128_f8f6f4 v[38:41], v[140:147], v[66:73], v[204:207], v189, v189 op_sel_hi:[0,0,0]
	v_mfma_scale_f32_16x16x128_f8f6f4 v[34:37], v[148:155], v[66:73], v[208:211], v189, v189 op_sel_hi:[0,0,0]
	s_setprio 0
	s_barrier
	s_add_i32 s78, s78, s16
	v_lshl_add_u64 v[26:27], v[184:185], 0, s[48:49]
	s_mov_b32 m0, s78
	ds_read_b128 v[18:21], v188 offset:49152
	ds_read_b128 v[22:25], v188 offset:50176
	ds_read_b128 v[156:159], v188 offset:51200
	ds_read_b128 v[160:163], v188 offset:52224
	ds_read_b128 v[164:167], v188 offset:53248
	ds_read_b128 v[168:171], v188 offset:54272
	ds_read_b128 v[172:175], v188 offset:55296
	ds_read_b128 v[176:179], v188 offset:56320
	global_load_lds_dwordx4 v[26:27], off
	v_lshl_add_u64 v[26:27], v[184:185], 0, s[50:51]
	s_add_i32 m0, s78, 0x2000
	s_add_i32 s78, s79, s16
	global_load_lds_dwordx4 v[26:27], off
	v_lshl_add_u64 v[26:27], v[184:185], 0, s[52:53]
	s_mov_b32 m0, s78
	s_nop 0
	global_load_lds_dwordx4 v[26:27], off
	v_lshl_add_u64 v[26:27], v[184:185], 0, s[66:67]
	s_add_i32 m0, s78, 0x2000
	s_nop 0
	global_load_lds_dwordx4 v[26:27], off
	v_lshl_add_u64 v[26:27], v[252:253], 0, s[48:49]
	s_mov_b32 m0, s59
	s_nop 0
	global_load_lds_dwordx4 v[26:27], off
	v_lshl_add_u64 v[26:27], v[252:253], 0, s[50:51]
	s_mov_b32 m0, s60
	s_nop 0
	global_load_lds_dwordx4 v[26:27], off
	s_waitcnt vmcnt(8)
	s_waitcnt lgkmcnt(0)
	s_barrier
	s_setprio 1
	s_waitcnt lgkmcnt(0)
	v_mfma_scale_f32_16x16x128_f8f6f4 v[94:97], v[2:9], v[18:25], v[94:97], v189, v189 op_sel_hi:[0,0,0]
	v_mfma_scale_f32_16x16x128_f8f6f4 v[90:93], v[10:17], v[18:25], v[90:93], v189, v189 op_sel_hi:[0,0,0]
	v_mfma_scale_f32_16x16x128_f8f6f4 v[86:89], v[2:9], v[156:163], v[86:89], v189, v189 op_sel_hi:[0,0,0]
	v_mfma_scale_f32_16x16x128_f8f6f4 v[82:85], v[10:17], v[156:163], v[82:85], v189, v189 op_sel_hi:[0,0,0]
	v_mfma_scale_f32_16x16x128_f8f6f4 v[78:81], v[2:9], v[164:171], v[78:81], v189, v189 op_sel_hi:[0,0,0]
	v_mfma_scale_f32_16x16x128_f8f6f4 v[74:77], v[10:17], v[164:171], v[74:77], v189, v189 op_sel_hi:[0,0,0]
	v_mfma_scale_f32_16x16x128_f8f6f4 v[70:73], v[2:9], v[172:179], v[212:215], v189, v189 op_sel_hi:[0,0,0]
	v_mfma_scale_f32_16x16x128_f8f6f4 v[66:69], v[10:17], v[172:179], v[216:219], v189, v189 op_sel_hi:[0,0,0]
	s_setprio 0
	s_setprio 1
	v_mfma_scale_f32_16x16x128_f8f6f4 v[30:33], v[140:147], v[18:25], v[220:223], v189, v189 op_sel_hi:[0,0,0]
	v_mfma_scale_f32_16x16x128_f8f6f4 v[26:29], v[148:155], v[18:25], v[224:227], v189, v189 op_sel_hi:[0,0,0]
	v_mfma_scale_f32_16x16x128_f8f6f4 v[22:25], v[140:147], v[156:163], v[228:231], v189, v189 op_sel_hi:[0,0,0]
	v_mfma_scale_f32_16x16x128_f8f6f4 v[18:21], v[148:155], v[156:163], v[232:235], v189, v189 op_sel_hi:[0,0,0]
	v_mfma_scale_f32_16x16x128_f8f6f4 v[14:17], v[140:147], v[164:171], v[236:239], v189, v189 op_sel_hi:[0,0,0]
	v_mfma_scale_f32_16x16x128_f8f6f4 v[10:13], v[148:155], v[164:171], v[240:243], v189, v189 op_sel_hi:[0,0,0]
	v_mfma_scale_f32_16x16x128_f8f6f4 v[6:9], v[140:147], v[172:179], v[244:247], v189, v189 op_sel_hi:[0,0,0]
	v_mfma_scale_f32_16x16x128_f8f6f4 v[2:5], v[148:155], v[172:179], v[248:251], v189, v189 op_sel_hi:[0,0,0]
	s_setprio 0
	s_barrier
	s_add_i32 s88, s88, 2
	s_add_u32 s86, s86, 0x100
	s_addc_u32 s87, s87, 0
	s_add_u32 s0, s0, 0x100
	s_addc_u32 s1, s1, 0
	s_cmp_gt_u32 s88, 19
	s_cbranch_scc1 .Lpeel_exit_275

.LBB0_347:
	s_ashr_i32 s83, s82, 31
	s_lshl_b64 s[34:35], s[82:83], 19
	s_add_u32 s94, s38, s34
	s_addc_u32 s95, s39, s35
	s_and_b64 s[34:35], s[4:5], exec
	s_cselect_b32 s1, s95, s7
	s_cselect_b32 s34, s94, s6
	s_ashr_i32 s87, s86, 31
	s_lshl_b64 s[96:97], s[86:87], 19
	s_add_u32 s35, s16, s96
	s_addc_u32 s83, s17, s97
	s_ashr_i32 s96, s82, 4
	s_ashr_i32 s97, s96, 31
	s_lshl_b64 s[96:97], s[96:97], 22
	s_add_u32 s96, s35, s96
	s_addc_u32 s97, s83, s97
	s_and_b64 vcc, s[4:5], exec
	s_cselect_b32 s35, s97, s85
	s_cselect_b32 s83, s96, s84
	s_add_u32 s6, s6, 0x40080
	.p2align 8
	s_addc_u32 s7, s7, 0
	s_add_u32 s84, s84, 0x100
	s_addc_u32 s85, s85, 0
	s_mov_b32 s87, -2
.Lpeel_348:
	s_waitcnt vmcnt(0)
	ds_read_b128 v[130:133], v202
	ds_read_b128 v[134:137], v202 offset:1024
	ds_read_b128 v[138:141], v202 offset:2048
	ds_read_b128 v[142:145], v202 offset:3072
	ds_read_b128 v[146:149], v203
	ds_read_b128 v[150:153], v203 offset:1024
	ds_read_b128 v[164:167], v203 offset:2048
	ds_read_b128 v[168:171], v203 offset:3072
	s_add_u32 s92, s6, 0xfffc0080
	s_addc_u32 s93, s7, -1
	s_cmp_eq_u32 s87, 12
	s_cselect_b32 vcc_hi, s1, s93
	s_cselect_b32 vcc_lo, s34, s92
	s_cselect_b32 s93, s35, s85
	s_cselect_b32 s92, s83, s84
	v_lshl_add_u64 v[200:201], s[6:7], 0, v[158:159]
	s_add_i32 m0, s58, 0xc000
	ds_read_b128 v[172:175], v204
	ds_read_b128 v[176:179], v204 offset:1024
	ds_read_b128 v[180:183], v204 offset:2048
	ds_read_b128 v[184:187], v204 offset:3072
	ds_read_b128 v[188:191], v204 offset:4096
	ds_read_b128 v[192:195], v204 offset:5120
	ds_read_b128 v[196:199], v204 offset:6144
	ds_read_b128 v[206:209], v204 offset:7168
	global_load_lds_dwordx4 v[200:201], off
	v_lshl_add_u64 v[200:201], v[200:201], 0, s[12:13]
	s_add_i32 m0, s58, 0xe000
	s_nop 0
	global_load_lds_dwordx4 v[200:201], off
	s_waitcnt vmcnt(8)
	s_waitcnt lgkmcnt(0)
	s_barrier
	s_setprio 1
	s_waitcnt lgkmcnt(0)
	v_mfma_f32_16x16x32_bf16 v[126:129], v[130:133], v[172:175], 0
	v_mfma_f32_16x16x32_bf16 v[122:125], v[138:141], v[172:175], 0
	v_mfma_f32_16x16x32_bf16 v[110:113], v[130:133], v[180:183], 0
	v_mfma_f32_16x16x32_bf16 v[106:109], v[138:141], v[180:183], 0
	v_mfma_f32_16x16x32_bf16 v[94:97], v[130:133], v[188:191], 0
	v_mfma_f32_16x16x32_bf16 v[90:93], v[138:141], v[188:191], 0
	v_mfma_f32_16x16x32_bf16 v[78:81], v[130:133], v[196:199], 0
	v_mfma_f32_16x16x32_bf16 v[74:77], v[138:141], v[196:199], 0
	v_mfma_f32_16x16x32_bf16 v[126:129], v[134:137], v[176:179], v[126:129]
	v_mfma_f32_16x16x32_bf16 v[122:125], v[142:145], v[176:179], v[122:125]
	v_mfma_f32_16x16x32_bf16 v[110:113], v[134:137], v[184:187], v[110:113]
	v_mfma_f32_16x16x32_bf16 v[106:109], v[142:145], v[184:187], v[106:109]
	v_mfma_f32_16x16x32_bf16 v[94:97], v[134:137], v[192:195], v[94:97]
	v_mfma_f32_16x16x32_bf16 v[90:93], v[142:145], v[192:195], v[90:93]
	v_mfma_f32_16x16x32_bf16 v[78:81], v[134:137], v[206:209], v[78:81]
	v_mfma_f32_16x16x32_bf16 v[74:77], v[142:145], v[206:209], v[74:77]
	s_setprio 0
	s_setprio 1
	v_mfma_f32_16x16x32_bf16 v[118:121], v[146:149], v[172:175], 0
	v_mfma_f32_16x16x32_bf16 v[114:117], v[164:167], v[172:175], 0
	v_mfma_f32_16x16x32_bf16 v[102:105], v[146:149], v[180:183], 0
	v_mfma_f32_16x16x32_bf16 v[98:101], v[164:167], v[180:183], 0
	v_mfma_f32_16x16x32_bf16 v[86:89], v[146:149], v[188:191], 0
	v_mfma_f32_16x16x32_bf16 v[82:85], v[164:167], v[188:191], 0
	v_mfma_f32_16x16x32_bf16 v[70:73], v[146:149], v[196:199], 0
	v_mfma_f32_16x16x32_bf16 v[66:69], v[164:167], v[196:199], 0
	v_mfma_f32_16x16x32_bf16 v[118:121], v[150:153], v[176:179], v[118:121]
	v_mfma_f32_16x16x32_bf16 v[114:117], v[168:171], v[176:179], v[114:117]
	v_mfma_f32_16x16x32_bf16 v[102:105], v[150:153], v[184:187], v[102:105]
	v_mfma_f32_16x16x32_bf16 v[98:101], v[168:171], v[184:187], v[98:101]
	v_mfma_f32_16x16x32_bf16 v[86:89], v[150:153], v[192:195], v[86:89]
	v_mfma_f32_16x16x32_bf16 v[82:85], v[168:171], v[192:195], v[82:85]
	v_mfma_f32_16x16x32_bf16 v[70:73], v[150:153], v[206:209], v[70:73]
	v_mfma_f32_16x16x32_bf16 v[66:69], v[168:171], v[206:209], v[66:69]
	s_setprio 0
	s_barrier
	v_lshl_add_u64 v[200:201], s[92:93], 0, v[156:157]
	s_add_i32 s92, s88, s33
	s_mov_b32 m0, s92
	ds_read_b128 v[172:175], v204 offset:16384
	ds_read_b128 v[176:179], v204 offset:17408
	ds_read_b128 v[180:183], v204 offset:18432
	ds_read_b128 v[184:187], v204 offset:19456
	ds_read_b128 v[188:191], v204 offset:20480
	ds_read_b128 v[192:195], v204 offset:21504
	ds_read_b128 v[196:199], v204 offset:22528
	ds_read_b128 v[206:209], v204 offset:23552
	global_load_lds_dwordx4 v[200:201], off
	v_lshl_add_u64 v[210:211], v[200:201], 0, s[12:13]
	s_add_i32 m0, s92, 0x2000
	s_add_i32 s92, s89, s33
	global_load_lds_dwordx4 v[210:211], off
	v_lshl_add_u64 v[210:211], v[200:201], 0, s[14:15]
	s_mov_b32 m0, s92
	s_nop 0
	global_load_lds_dwordx4 v[210:211], off
	v_lshl_add_u64 v[210:211], v[200:201], 0, s[44:45]
	s_add_i32 m0, s92, 0x2000
	s_nop 0
	global_load_lds_dwordx4 v[210:211], off
	v_lshl_add_u64 v[210:211], vcc, 0, v[154:155]
	s_mov_b32 m0, s58
	v_lshl_add_u64 v[212:213], v[210:211], 0, s[12:13]
	global_load_lds_dwordx4 v[210:211], off
	s_mov_b32 m0, s59
	s_nop 0
	global_load_lds_dwordx4 v[212:213], off
	s_waitcnt vmcnt(8)
	s_waitcnt lgkmcnt(0)
	s_barrier
	s_setprio 1
	s_waitcnt lgkmcnt(0)
	v_mfma_f32_16x16x32_bf16 v[62:65], v[130:133], v[172:175], 0
	v_mfma_f32_16x16x32_bf16 v[58:61], v[138:141], v[172:175], 0
	v_mfma_f32_16x16x32_bf16 v[46:49], v[130:133], v[180:183], 0
	v_mfma_f32_16x16x32_bf16 v[42:45], v[138:141], v[180:183], 0
	v_mfma_f32_16x16x32_bf16 v[30:33], v[130:133], v[188:191], 0
	v_mfma_f32_16x16x32_bf16 v[26:29], v[138:141], v[188:191], 0
	v_mfma_f32_16x16x32_bf16 v[14:17], v[130:133], v[196:199], 0
	v_mfma_f32_16x16x32_bf16 v[10:13], v[138:141], v[196:199], 0
	v_mfma_f32_16x16x32_bf16 v[62:65], v[134:137], v[176:179], v[62:65]
	v_mfma_f32_16x16x32_bf16 v[58:61], v[142:145], v[176:179], v[58:61]
	v_mfma_f32_16x16x32_bf16 v[46:49], v[134:137], v[184:187], v[46:49]
	v_mfma_f32_16x16x32_bf16 v[42:45], v[142:145], v[184:187], v[42:45]
	v_mfma_f32_16x16x32_bf16 v[30:33], v[134:137], v[192:195], v[30:33]
	v_mfma_f32_16x16x32_bf16 v[26:29], v[142:145], v[192:195], v[26:29]
	v_mfma_f32_16x16x32_bf16 v[14:17], v[134:137], v[206:209], v[14:17]
	v_mfma_f32_16x16x32_bf16 v[10:13], v[142:145], v[206:209], v[10:13]
	s_setprio 0
	s_setprio 1
	v_mfma_f32_16x16x32_bf16 v[54:57], v[146:149], v[172:175], 0
	v_mfma_f32_16x16x32_bf16 v[50:53], v[164:167], v[172:175], 0
	v_mfma_f32_16x16x32_bf16 v[38:41], v[146:149], v[180:183], 0
	v_mfma_f32_16x16x32_bf16 v[34:37], v[164:167], v[180:183], 0
	v_mfma_f32_16x16x32_bf16 v[22:25], v[146:149], v[188:191], 0
	v_mfma_f32_16x16x32_bf16 v[18:21], v[164:167], v[188:191], 0
	v_mfma_f32_16x16x32_bf16 v[6:9], v[146:149], v[196:199], 0
	v_mfma_f32_16x16x32_bf16 v[2:5], v[164:167], v[196:199], 0
	v_mfma_f32_16x16x32_bf16 v[54:57], v[150:153], v[176:179], v[54:57]
	v_mfma_f32_16x16x32_bf16 v[50:53], v[168:171], v[176:179], v[50:53]
	v_mfma_f32_16x16x32_bf16 v[38:41], v[150:153], v[184:187], v[38:41]
	v_mfma_f32_16x16x32_bf16 v[34:37], v[168:171], v[184:187], v[34:37]
	v_mfma_f32_16x16x32_bf16 v[22:25], v[150:153], v[192:195], v[22:25]
	v_mfma_f32_16x16x32_bf16 v[18:21], v[168:171], v[192:195], v[18:21]
	v_mfma_f32_16x16x32_bf16 v[6:9], v[150:153], v[206:209], v[6:9]
	v_mfma_f32_16x16x32_bf16 v[2:5], v[168:171], v[206:209], v[2:5]
	s_setprio 0
	s_barrier
	s_add_i32 s92, 0, 0x18000
	s_add_i32 s93, 0, 0x1c000
	v_add_u32_e32 v142, s92, v1
	v_add_u32_e32 v168, s93, v1
	ds_read_b128 v[130:133], v142
	ds_read_b128 v[134:137], v142 offset:1024
	ds_read_b128 v[138:141], v142 offset:2048
	ds_read_b128 v[142:145], v142 offset:3072
	ds_read_b128 v[146:149], v168
	ds_read_b128 v[150:153], v168 offset:1024
	ds_read_b128 v[164:167], v168 offset:2048
	ds_read_b128 v[168:171], v168 offset:3072
	s_mov_b32 m0, s60
	v_lshl_add_u64 v[212:213], v[210:211], 0, s[14:15]
	ds_read_b128 v[172:175], v204 offset:32768
	ds_read_b128 v[176:179], v204 offset:33792
	ds_read_b128 v[180:183], v204 offset:34816
	ds_read_b128 v[184:187], v204 offset:35840
	ds_read_b128 v[188:191], v204 offset:36864
	ds_read_b128 v[192:195], v204 offset:37888
	ds_read_b128 v[196:199], v204 offset:38912
	ds_read_b128 v[206:209], v204 offset:39936
	global_load_lds_dwordx4 v[212:213], off
	v_lshl_add_u64 v[212:213], v[210:211], 0, s[44:45]
	s_mov_b32 m0, s61
	s_nop 0
	global_load_lds_dwordx4 v[212:213], off
	s_waitcnt vmcnt(8)
	s_waitcnt lgkmcnt(0)
	s_barrier
	s_setprio 1
	s_waitcnt lgkmcnt(0)
	v_mfma_f32_16x16x32_bf16 v[126:129], v[130:133], v[172:175], v[126:129]
	v_mfma_f32_16x16x32_bf16 v[122:125], v[138:141], v[172:175], v[122:125]
	v_mfma_f32_16x16x32_bf16 v[110:113], v[130:133], v[180:183], v[110:113]
	v_mfma_f32_16x16x32_bf16 v[106:109], v[138:141], v[180:183], v[106:109]
	v_mfma_f32_16x16x32_bf16 v[94:97], v[130:133], v[188:191], v[94:97]
	v_mfma_f32_16x16x32_bf16 v[90:93], v[138:141], v[188:191], v[90:93]
	v_mfma_f32_16x16x32_bf16 v[78:81], v[130:133], v[196:199], v[78:81]
	v_mfma_f32_16x16x32_bf16 v[74:77], v[138:141], v[196:199], v[74:77]
	v_mfma_f32_16x16x32_bf16 v[126:129], v[134:137], v[176:179], v[126:129]
	v_mfma_f32_16x16x32_bf16 v[122:125], v[142:145], v[176:179], v[122:125]
	v_mfma_f32_16x16x32_bf16 v[110:113], v[134:137], v[184:187], v[110:113]
	v_mfma_f32_16x16x32_bf16 v[106:109], v[142:145], v[184:187], v[106:109]
	v_mfma_f32_16x16x32_bf16 v[94:97], v[134:137], v[192:195], v[94:97]
	v_mfma_f32_16x16x32_bf16 v[90:93], v[142:145], v[192:195], v[90:93]
	v_mfma_f32_16x16x32_bf16 v[78:81], v[134:137], v[206:209], v[78:81]
	v_mfma_f32_16x16x32_bf16 v[74:77], v[142:145], v[206:209], v[74:77]
	s_setprio 0
	s_setprio 1
	v_mfma_f32_16x16x32_bf16 v[118:121], v[146:149], v[172:175], v[118:121]
	v_mfma_f32_16x16x32_bf16 v[114:117], v[164:167], v[172:175], v[114:117]
	v_mfma_f32_16x16x32_bf16 v[102:105], v[146:149], v[180:183], v[102:105]
	v_mfma_f32_16x16x32_bf16 v[98:101], v[164:167], v[180:183], v[98:101]
	v_mfma_f32_16x16x32_bf16 v[86:89], v[146:149], v[188:191], v[86:89]
	v_mfma_f32_16x16x32_bf16 v[82:85], v[164:167], v[188:191], v[82:85]
	v_mfma_f32_16x16x32_bf16 v[70:73], v[146:149], v[196:199], v[70:73]
	v_mfma_f32_16x16x32_bf16 v[66:69], v[164:167], v[196:199], v[66:69]
	v_mfma_f32_16x16x32_bf16 v[118:121], v[150:153], v[176:179], v[118:121]
	v_mfma_f32_16x16x32_bf16 v[114:117], v[168:171], v[176:179], v[114:117]
	v_mfma_f32_16x16x32_bf16 v[102:105], v[150:153], v[184:187], v[102:105]
	v_mfma_f32_16x16x32_bf16 v[98:101], v[168:171], v[184:187], v[98:101]
	v_mfma_f32_16x16x32_bf16 v[86:89], v[150:153], v[192:195], v[86:89]
	v_mfma_f32_16x16x32_bf16 v[82:85], v[168:171], v[192:195], v[82:85]
	v_mfma_f32_16x16x32_bf16 v[70:73], v[150:153], v[206:209], v[70:73]
	v_mfma_f32_16x16x32_bf16 v[66:69], v[168:171], v[206:209], v[66:69]
	s_setprio 0
	s_barrier
	s_add_i32 s92, s92, s33
	v_lshl_add_u64 v[212:213], v[200:201], 0, s[50:51]
	s_mov_b32 m0, s92
	ds_read_b128 v[172:175], v204 offset:49152
	ds_read_b128 v[176:179], v204 offset:50176
	ds_read_b128 v[180:183], v204 offset:51200
	ds_read_b128 v[184:187], v204 offset:52224
	ds_read_b128 v[188:191], v204 offset:53248
	ds_read_b128 v[192:195], v204 offset:54272
	ds_read_b128 v[196:199], v204 offset:55296
	ds_read_b128 v[206:209], v204 offset:56320
	global_load_lds_dwordx4 v[212:213], off
	v_lshl_add_u64 v[212:213], v[200:201], 0, s[52:53]
	s_add_i32 m0, s92, 0x2000
	s_add_i32 s92, s93, s33
	global_load_lds_dwordx4 v[212:213], off
	v_lshl_add_u64 v[212:213], v[200:201], 0, s[66:67]
	s_mov_b32 m0, s92
	v_lshl_add_u64 v[200:201], v[200:201], 0, s[68:69]
	global_load_lds_dwordx4 v[212:213], off
	s_add_i32 m0, s92, 0x2000
	s_nop 0
	global_load_lds_dwordx4 v[200:201], off
	v_lshl_add_u64 v[200:201], v[210:211], 0, s[50:51]
	s_mov_b32 m0, s79
	s_nop 0
	global_load_lds_dwordx4 v[200:201], off
	v_lshl_add_u64 v[200:201], v[210:211], 0, s[52:53]
	s_mov_b32 m0, s81
	s_nop 0
	global_load_lds_dwordx4 v[200:201], off
	s_waitcnt vmcnt(8)
	s_waitcnt lgkmcnt(0)
	s_barrier
	s_setprio 1
	s_waitcnt lgkmcnt(0)
	v_mfma_f32_16x16x32_bf16 v[62:65], v[130:133], v[172:175], v[62:65]
	v_mfma_f32_16x16x32_bf16 v[58:61], v[138:141], v[172:175], v[58:61]
	v_mfma_f32_16x16x32_bf16 v[46:49], v[130:133], v[180:183], v[46:49]
	v_mfma_f32_16x16x32_bf16 v[42:45], v[138:141], v[180:183], v[42:45]
	v_mfma_f32_16x16x32_bf16 v[30:33], v[130:133], v[188:191], v[30:33]
	v_mfma_f32_16x16x32_bf16 v[26:29], v[138:141], v[188:191], v[26:29]
	v_mfma_f32_16x16x32_bf16 v[14:17], v[130:133], v[196:199], v[14:17]
	v_mfma_f32_16x16x32_bf16 v[10:13], v[138:141], v[196:199], v[10:13]
	v_mfma_f32_16x16x32_bf16 v[62:65], v[134:137], v[176:179], v[62:65]
	v_mfma_f32_16x16x32_bf16 v[58:61], v[142:145], v[176:179], v[58:61]
	v_mfma_f32_16x16x32_bf16 v[46:49], v[134:137], v[184:187], v[46:49]
	v_mfma_f32_16x16x32_bf16 v[42:45], v[142:145], v[184:187], v[42:45]
	v_mfma_f32_16x16x32_bf16 v[30:33], v[134:137], v[192:195], v[30:33]
	v_mfma_f32_16x16x32_bf16 v[26:29], v[142:145], v[192:195], v[26:29]
	v_mfma_f32_16x16x32_bf16 v[14:17], v[134:137], v[206:209], v[14:17]
	v_mfma_f32_16x16x32_bf16 v[10:13], v[142:145], v[206:209], v[10:13]
	s_setprio 0
	s_setprio 1
	v_mfma_f32_16x16x32_bf16 v[54:57], v[146:149], v[172:175], v[54:57]
	v_mfma_f32_16x16x32_bf16 v[50:53], v[164:167], v[172:175], v[50:53]
	v_mfma_f32_16x16x32_bf16 v[38:41], v[146:149], v[180:183], v[38:41]
	v_mfma_f32_16x16x32_bf16 v[34:37], v[164:167], v[180:183], v[34:37]
	v_mfma_f32_16x16x32_bf16 v[22:25], v[146:149], v[188:191], v[22:25]
	v_mfma_f32_16x16x32_bf16 v[18:21], v[164:167], v[188:191], v[18:21]
	v_mfma_f32_16x16x32_bf16 v[6:9], v[146:149], v[196:199], v[6:9]
	v_mfma_f32_16x16x32_bf16 v[2:5], v[164:167], v[196:199], v[2:5]
	v_mfma_f32_16x16x32_bf16 v[54:57], v[150:153], v[176:179], v[54:57]
	v_mfma_f32_16x16x32_bf16 v[50:53], v[168:171], v[176:179], v[50:53]
	v_mfma_f32_16x16x32_bf16 v[38:41], v[150:153], v[184:187], v[38:41]
	v_mfma_f32_16x16x32_bf16 v[34:37], v[168:171], v[184:187], v[34:37]
	v_mfma_f32_16x16x32_bf16 v[22:25], v[150:153], v[192:195], v[22:25]
	v_mfma_f32_16x16x32_bf16 v[18:21], v[168:171], v[192:195], v[18:21]
	v_mfma_f32_16x16x32_bf16 v[6:9], v[150:153], v[206:209], v[6:9]
	v_mfma_f32_16x16x32_bf16 v[2:5], v[168:171], v[206:209], v[2:5]
	s_setprio 0
	s_barrier
	s_add_i32 s87, s87, 2
	s_add_u32 s6, s6, 0x100
	s_addc_u32 s7, s7, 0
	s_add_u32 s84, s84, 0x100
	s_addc_u32 s85, s85, 0
	s_cmp_gt_u32 s87, 13
	s_cbranch_scc1 .Lpeel_exit_348

.LBB0_567:
	s_ashr_i32 s59, s58, 31
	s_mov_b32 s27, s24
	s_lshl_b64 s[34:35], s[58:59], 19
	v_readlane_b32 s24, v254, 58
	s_add_u32 s36, s24, s34
	v_readlane_b32 s24, v254, 61
	s_addc_u32 s37, s24, s35
	s_and_b64 s[34:35], s[4:5], exec
	s_cselect_b32 s34, s37, s69
	s_cselect_b32 s35, s36, s68
	s_ashr_i32 s57, s56, 31
	s_lshl_b64 s[62:63], s[56:57], 19
	v_readlane_b32 s70, v254, 33
	v_readlane_b32 s71, v254, 34
	s_add_u32 s24, s70, s62
	s_mov_b32 s18, s25
	s_addc_u32 s25, s71, s63
	s_and_b64 s[70:71], s[4:5], exec
	s_cselect_b32 s40, s25, s1
	s_cselect_b32 s57, s24, s0
	s_add_u32 s59, s0, 0x100
	.p2align 8
	s_addc_u32 s67, s1, 0
	s_add_u32 s0, s68, 0x40080
	s_addc_u32 s1, s69, 0
	s_mov_b32 s68, -2
.Lpeel_568:
	ds_read_b128 v[130:133], v236
	ds_read_b128 v[134:137], v236 offset:1024
	ds_read_b128 v[138:141], v236 offset:2048
	ds_read_b128 v[142:145], v236 offset:3072
	ds_read_b128 v[146:149], v237
	ds_read_b128 v[150:153], v237 offset:1024
	ds_read_b128 v[154:157], v237 offset:2048
	ds_read_b128 v[158:161], v237 offset:3072
	s_add_u32 s69, s0, 0xfffc0080
	s_addc_u32 s70, s1, -1
	s_cmp_eq_u32 s68, 12
	s_cselect_b32 s71, s34, s70
	s_cselect_b32 s70, s35, s69
	s_cselect_b32 s73, s40, s67
	s_cselect_b32 s72, s57, s59
	v_lshl_add_u64 v[172:173], s[0:1], 0, v[170:171]
	s_add_i32 m0, s17, 0xc000
	ds_read_b128 v[162:165], v238
	ds_read_b128 v[176:179], v238 offset:1024
	ds_read_b128 v[180:183], v238 offset:2048
	ds_read_b128 v[184:187], v238 offset:3072
	ds_read_b128 v[188:191], v238 offset:4096
	ds_read_b128 v[192:195], v238 offset:5120
	ds_read_b128 v[196:199], v238 offset:6144
	ds_read_b128 v[200:203], v238 offset:7168
	global_load_lds_dwordx4 v[172:173], off
	v_lshl_add_u64 v[172:173], v[172:173], 0, s[10:11]
	s_add_i32 m0, s17, 0xe000
	s_nop 0
	global_load_lds_dwordx4 v[172:173], off
	s_waitcnt vmcnt(8)
	s_waitcnt lgkmcnt(0)
	s_barrier
	s_setprio 1
	s_waitcnt lgkmcnt(0)
	v_mfma_f32_16x16x32_bf16 v[126:129], v[130:133], v[162:165], 0
	v_mfma_f32_16x16x32_bf16 v[122:125], v[138:141], v[162:165], 0
	v_mfma_f32_16x16x32_bf16 v[118:121], v[130:133], v[180:183], 0
	v_mfma_f32_16x16x32_bf16 v[114:117], v[138:141], v[180:183], 0
	v_mfma_f32_16x16x32_bf16 v[110:113], v[130:133], v[188:191], 0
	v_mfma_f32_16x16x32_bf16 v[106:109], v[138:141], v[188:191], 0
	v_mfma_f32_16x16x32_bf16 v[102:105], v[130:133], v[196:199], 0
	v_mfma_f32_16x16x32_bf16 v[98:101], v[138:141], v[196:199], 0
	v_mfma_f32_16x16x32_bf16 v[126:129], v[134:137], v[176:179], v[126:129]
	v_mfma_f32_16x16x32_bf16 v[122:125], v[142:145], v[176:179], v[122:125]
	v_mfma_f32_16x16x32_bf16 v[118:121], v[134:137], v[184:187], v[118:121]
	v_mfma_f32_16x16x32_bf16 v[114:117], v[142:145], v[184:187], v[114:117]
	v_mfma_f32_16x16x32_bf16 v[110:113], v[134:137], v[192:195], v[110:113]
	v_mfma_f32_16x16x32_bf16 v[106:109], v[142:145], v[192:195], v[106:109]
	v_mfma_f32_16x16x32_bf16 v[102:105], v[134:137], v[200:203], v[102:105]
	v_mfma_f32_16x16x32_bf16 v[98:101], v[142:145], v[200:203], v[98:101]
	s_setprio 0
	s_setprio 1
	v_mfma_f32_16x16x32_bf16 v[70:73], v[146:149], v[162:165], 0
	v_mfma_f32_16x16x32_bf16 v[62:65], v[154:157], v[162:165], 0
	v_mfma_f32_16x16x32_bf16 v[54:57], v[146:149], v[180:183], 0
	v_mfma_f32_16x16x32_bf16 v[50:53], v[154:157], v[180:183], 0
	v_mfma_f32_16x16x32_bf16 v[46:49], v[146:149], v[188:191], 0
	v_mfma_f32_16x16x32_bf16 v[42:45], v[154:157], v[188:191], 0
	v_mfma_f32_16x16x32_bf16 v[38:41], v[146:149], v[196:199], 0
	v_mfma_f32_16x16x32_bf16 v[34:37], v[154:157], v[196:199], 0
	v_mfma_f32_16x16x32_bf16 v[70:73], v[150:153], v[176:179], v[70:73]
	v_mfma_f32_16x16x32_bf16 v[62:65], v[158:161], v[176:179], v[62:65]
	v_mfma_f32_16x16x32_bf16 v[54:57], v[150:153], v[184:187], v[54:57]
	v_mfma_f32_16x16x32_bf16 v[50:53], v[158:161], v[184:187], v[50:53]
	v_mfma_f32_16x16x32_bf16 v[46:49], v[150:153], v[192:195], v[46:49]
	v_mfma_f32_16x16x32_bf16 v[42:45], v[158:161], v[192:195], v[42:45]
	v_mfma_f32_16x16x32_bf16 v[38:41], v[150:153], v[200:203], v[38:41]
	v_mfma_f32_16x16x32_bf16 v[34:37], v[158:161], v[200:203], v[34:37]
	s_setprio 0
	s_barrier
	s_add_i32 s69, s94, s16
	v_lshl_add_u64 v[172:173], s[72:73], 0, v[168:169]
	s_mov_b32 m0, s69
	ds_read_b128 v[162:165], v238 offset:16384
	ds_read_b128 v[176:179], v238 offset:17408
	ds_read_b128 v[180:183], v238 offset:18432
	ds_read_b128 v[184:187], v238 offset:19456
	ds_read_b128 v[188:191], v238 offset:20480
	ds_read_b128 v[192:195], v238 offset:21504
	ds_read_b128 v[196:199], v238 offset:22528
	ds_read_b128 v[200:203], v238 offset:23552
	global_load_lds_dwordx4 v[172:173], off
	v_lshl_add_u64 v[174:175], v[172:173], 0, s[10:11]
	s_add_i32 m0, s69, 0x2000
	s_add_i32 s69, s95, s16
	global_load_lds_dwordx4 v[174:175], off
	v_lshl_add_u64 v[174:175], v[172:173], 0, s[12:13]
	s_mov_b32 m0, s69
	s_nop 0
	global_load_lds_dwordx4 v[174:175], off
	v_lshl_add_u64 v[174:175], v[172:173], 0, s[14:15]
	s_add_i32 m0, s69, 0x2000
	s_nop 0
	global_load_lds_dwordx4 v[174:175], off
	v_lshl_add_u64 v[174:175], s[70:71], 0, v[166:167]
	s_mov_b32 m0, s17
	v_lshl_add_u64 v[204:205], v[174:175], 0, s[10:11]
	global_load_lds_dwordx4 v[174:175], off
	s_mov_b32 m0, s33
	s_nop 0
	global_load_lds_dwordx4 v[204:205], off
	s_waitcnt vmcnt(8)
	s_waitcnt lgkmcnt(0)
	s_barrier
	s_setprio 1
	s_waitcnt lgkmcnt(0)
	v_mfma_f32_16x16x32_bf16 v[94:97], v[130:133], v[162:165], 0
	v_mfma_f32_16x16x32_bf16 v[90:93], v[138:141], v[162:165], 0
	v_mfma_f32_16x16x32_bf16 v[86:89], v[130:133], v[180:183], 0
	v_mfma_f32_16x16x32_bf16 v[82:85], v[138:141], v[180:183], 0
	v_mfma_f32_16x16x32_bf16 v[78:81], v[130:133], v[188:191], 0
	v_mfma_f32_16x16x32_bf16 v[74:77], v[138:141], v[188:191], 0
	v_mfma_f32_16x16x32_bf16 v[66:69], v[130:133], v[196:199], 0
	v_mfma_f32_16x16x32_bf16 v[58:61], v[138:141], v[196:199], 0
	v_mfma_f32_16x16x32_bf16 v[94:97], v[134:137], v[176:179], v[94:97]
	v_mfma_f32_16x16x32_bf16 v[90:93], v[142:145], v[176:179], v[90:93]
	v_mfma_f32_16x16x32_bf16 v[86:89], v[134:137], v[184:187], v[86:89]
	v_mfma_f32_16x16x32_bf16 v[82:85], v[142:145], v[184:187], v[82:85]
	v_mfma_f32_16x16x32_bf16 v[78:81], v[134:137], v[192:195], v[78:81]
	v_mfma_f32_16x16x32_bf16 v[74:77], v[142:145], v[192:195], v[74:77]
	v_mfma_f32_16x16x32_bf16 v[66:69], v[134:137], v[200:203], v[66:69]
	v_mfma_f32_16x16x32_bf16 v[58:61], v[142:145], v[200:203], v[58:61]
	s_setprio 0
	s_setprio 1
	v_mfma_f32_16x16x32_bf16 v[30:33], v[146:149], v[162:165], 0
	v_mfma_f32_16x16x32_bf16 v[26:29], v[154:157], v[162:165], 0
	v_mfma_f32_16x16x32_bf16 v[22:25], v[146:149], v[180:183], 0
	v_mfma_f32_16x16x32_bf16 v[18:21], v[154:157], v[180:183], 0
	v_mfma_f32_16x16x32_bf16 v[14:17], v[146:149], v[188:191], 0
	v_mfma_f32_16x16x32_bf16 v[10:13], v[154:157], v[188:191], 0
	v_mfma_f32_16x16x32_bf16 v[6:9], v[146:149], v[196:199], 0
	v_mfma_f32_16x16x32_bf16 v[2:5], v[154:157], v[196:199], 0
	v_mfma_f32_16x16x32_bf16 v[30:33], v[150:153], v[176:179], v[30:33]
	v_mfma_f32_16x16x32_bf16 v[26:29], v[158:161], v[176:179], v[26:29]
	v_mfma_f32_16x16x32_bf16 v[22:25], v[150:153], v[184:187], v[22:25]
	v_mfma_f32_16x16x32_bf16 v[18:21], v[158:161], v[184:187], v[18:21]
	v_mfma_f32_16x16x32_bf16 v[14:17], v[150:153], v[192:195], v[14:17]
	v_mfma_f32_16x16x32_bf16 v[10:13], v[158:161], v[192:195], v[10:13]
	v_mfma_f32_16x16x32_bf16 v[6:9], v[150:153], v[200:203], v[6:9]
	v_mfma_f32_16x16x32_bf16 v[2:5], v[158:161], v[200:203], v[2:5]
	s_setprio 0
	s_barrier
	s_add_i32 s69, 0, 0x18000
	s_add_i32 s70, 0, 0x1c000
	v_add_u32_e32 v142, s69, v1
	v_add_u32_e32 v158, s70, v1
	ds_read_b128 v[130:133], v142
	ds_read_b128 v[134:137], v142 offset:1024
	ds_read_b128 v[138:141], v142 offset:2048
	ds_read_b128 v[142:145], v142 offset:3072
	ds_read_b128 v[146:149], v158
	ds_read_b128 v[150:153], v158 offset:1024
	ds_read_b128 v[154:157], v158 offset:2048
	ds_read_b128 v[158:161], v158 offset:3072
	s_mov_b32 m0, s19
	v_lshl_add_u64 v[204:205], v[174:175], 0, s[12:13]
	ds_read_b128 v[162:165], v238 offset:32768
	ds_read_b128 v[176:179], v238 offset:33792
	ds_read_b128 v[180:183], v238 offset:34816
	ds_read_b128 v[184:187], v238 offset:35840
	ds_read_b128 v[188:191], v238 offset:36864
	ds_read_b128 v[192:195], v238 offset:37888
	ds_read_b128 v[196:199], v238 offset:38912
	ds_read_b128 v[200:203], v238 offset:39936
	global_load_lds_dwordx4 v[204:205], off
	v_lshl_add_u64 v[204:205], v[174:175], 0, s[14:15]
	s_mov_b32 m0, s76
	s_nop 0
	global_load_lds_dwordx4 v[204:205], off
	s_waitcnt vmcnt(8)
	s_waitcnt lgkmcnt(0)
	s_barrier
	s_setprio 1
	s_waitcnt lgkmcnt(0)
	v_mfma_f32_16x16x32_bf16 v[126:129], v[130:133], v[162:165], v[126:129]
	v_mfma_f32_16x16x32_bf16 v[122:125], v[138:141], v[162:165], v[122:125]
	v_mfma_f32_16x16x32_bf16 v[118:121], v[130:133], v[180:183], v[118:121]
	v_mfma_f32_16x16x32_bf16 v[114:117], v[138:141], v[180:183], v[114:117]
	v_mfma_f32_16x16x32_bf16 v[110:113], v[130:133], v[188:191], v[110:113]
	v_mfma_f32_16x16x32_bf16 v[106:109], v[138:141], v[188:191], v[106:109]
	v_mfma_f32_16x16x32_bf16 v[102:105], v[130:133], v[196:199], v[102:105]
	v_mfma_f32_16x16x32_bf16 v[98:101], v[138:141], v[196:199], v[98:101]
	v_mfma_f32_16x16x32_bf16 v[126:129], v[134:137], v[176:179], v[126:129]
	v_mfma_f32_16x16x32_bf16 v[122:125], v[142:145], v[176:179], v[122:125]
	v_mfma_f32_16x16x32_bf16 v[118:121], v[134:137], v[184:187], v[118:121]
	v_mfma_f32_16x16x32_bf16 v[114:117], v[142:145], v[184:187], v[114:117]
	v_mfma_f32_16x16x32_bf16 v[110:113], v[134:137], v[192:195], v[110:113]
	v_mfma_f32_16x16x32_bf16 v[106:109], v[142:145], v[192:195], v[106:109]
	v_mfma_f32_16x16x32_bf16 v[102:105], v[134:137], v[200:203], v[102:105]
	v_mfma_f32_16x16x32_bf16 v[98:101], v[142:145], v[200:203], v[98:101]
	s_setprio 0
	s_setprio 1
	v_mfma_f32_16x16x32_bf16 v[70:73], v[146:149], v[162:165], v[70:73]
	v_mfma_f32_16x16x32_bf16 v[62:65], v[154:157], v[162:165], v[62:65]
	v_mfma_f32_16x16x32_bf16 v[54:57], v[146:149], v[180:183], v[54:57]
	v_mfma_f32_16x16x32_bf16 v[50:53], v[154:157], v[180:183], v[50:53]
	v_mfma_f32_16x16x32_bf16 v[46:49], v[146:149], v[188:191], v[46:49]
	v_mfma_f32_16x16x32_bf16 v[42:45], v[154:157], v[188:191], v[42:45]
	v_mfma_f32_16x16x32_bf16 v[38:41], v[146:149], v[196:199], v[38:41]
	v_mfma_f32_16x16x32_bf16 v[34:37], v[154:157], v[196:199], v[34:37]
	v_mfma_f32_16x16x32_bf16 v[70:73], v[150:153], v[176:179], v[70:73]
	v_mfma_f32_16x16x32_bf16 v[62:65], v[158:161], v[176:179], v[62:65]
	v_mfma_f32_16x16x32_bf16 v[54:57], v[150:153], v[184:187], v[54:57]
	v_mfma_f32_16x16x32_bf16 v[50:53], v[158:161], v[184:187], v[50:53]
	v_mfma_f32_16x16x32_bf16 v[46:49], v[150:153], v[192:195], v[46:49]
	v_mfma_f32_16x16x32_bf16 v[42:45], v[158:161], v[192:195], v[42:45]
	v_mfma_f32_16x16x32_bf16 v[38:41], v[150:153], v[200:203], v[38:41]
	v_mfma_f32_16x16x32_bf16 v[34:37], v[158:161], v[200:203], v[34:37]
	s_setprio 0
	s_barrier
	s_add_i32 s69, s69, s16
	v_lshl_add_u64 v[204:205], v[172:173], 0, s[44:45]
	s_mov_b32 m0, s69
	ds_read_b128 v[162:165], v238 offset:49152
	ds_read_b128 v[176:179], v238 offset:50176
	ds_read_b128 v[180:183], v238 offset:51200
	ds_read_b128 v[184:187], v238 offset:52224
	ds_read_b128 v[188:191], v238 offset:53248
	ds_read_b128 v[192:195], v238 offset:54272
	ds_read_b128 v[196:199], v238 offset:55296
	ds_read_b128 v[200:203], v238 offset:56320
	global_load_lds_dwordx4 v[204:205], off
	v_lshl_add_u64 v[204:205], v[172:173], 0, s[48:49]
	s_add_i32 m0, s69, 0x2000
	s_add_i32 s69, s70, s16
	global_load_lds_dwordx4 v[204:205], off
	v_lshl_add_u64 v[204:205], v[172:173], 0, s[50:51]
	s_mov_b32 m0, s69
	v_lshl_add_u64 v[172:173], v[172:173], 0, s[52:53]
	global_load_lds_dwordx4 v[204:205], off
	s_add_i32 m0, s69, 0x2000
	s_nop 0
	global_load_lds_dwordx4 v[172:173], off
	v_lshl_add_u64 v[172:173], v[174:175], 0, s[44:45]
	s_mov_b32 m0, s87
	s_nop 0
	global_load_lds_dwordx4 v[172:173], off
	v_lshl_add_u64 v[172:173], v[174:175], 0, s[48:49]
	s_mov_b32 m0, s88
	s_nop 0
	global_load_lds_dwordx4 v[172:173], off
	s_waitcnt vmcnt(8)
	s_waitcnt lgkmcnt(0)
	s_barrier
	s_setprio 1
	s_waitcnt lgkmcnt(0)
	v_mfma_f32_16x16x32_bf16 v[94:97], v[130:133], v[162:165], v[94:97]
	v_mfma_f32_16x16x32_bf16 v[90:93], v[138:141], v[162:165], v[90:93]
	v_mfma_f32_16x16x32_bf16 v[86:89], v[130:133], v[180:183], v[86:89]
	v_mfma_f32_16x16x32_bf16 v[82:85], v[138:141], v[180:183], v[82:85]
	v_mfma_f32_16x16x32_bf16 v[78:81], v[130:133], v[188:191], v[78:81]
	v_mfma_f32_16x16x32_bf16 v[74:77], v[138:141], v[188:191], v[74:77]
	v_mfma_f32_16x16x32_bf16 v[66:69], v[130:133], v[196:199], v[66:69]
	v_mfma_f32_16x16x32_bf16 v[58:61], v[138:141], v[196:199], v[58:61]
	v_mfma_f32_16x16x32_bf16 v[94:97], v[134:137], v[176:179], v[94:97]
	v_mfma_f32_16x16x32_bf16 v[90:93], v[142:145], v[176:179], v[90:93]
	v_mfma_f32_16x16x32_bf16 v[86:89], v[134:137], v[184:187], v[86:89]
	v_mfma_f32_16x16x32_bf16 v[82:85], v[142:145], v[184:187], v[82:85]
	v_mfma_f32_16x16x32_bf16 v[78:81], v[134:137], v[192:195], v[78:81]
	v_mfma_f32_16x16x32_bf16 v[74:77], v[142:145], v[192:195], v[74:77]
	v_mfma_f32_16x16x32_bf16 v[66:69], v[134:137], v[200:203], v[66:69]
	v_mfma_f32_16x16x32_bf16 v[58:61], v[142:145], v[200:203], v[58:61]
	s_setprio 0
	s_setprio 1
	v_mfma_f32_16x16x32_bf16 v[30:33], v[146:149], v[162:165], v[30:33]
	v_mfma_f32_16x16x32_bf16 v[26:29], v[154:157], v[162:165], v[26:29]
	v_mfma_f32_16x16x32_bf16 v[22:25], v[146:149], v[180:183], v[22:25]
	v_mfma_f32_16x16x32_bf16 v[18:21], v[154:157], v[180:183], v[18:21]
	v_mfma_f32_16x16x32_bf16 v[14:17], v[146:149], v[188:191], v[14:17]
	v_mfma_f32_16x16x32_bf16 v[10:13], v[154:157], v[188:191], v[10:13]
	v_mfma_f32_16x16x32_bf16 v[6:9], v[146:149], v[196:199], v[6:9]
	v_mfma_f32_16x16x32_bf16 v[2:5], v[154:157], v[196:199], v[2:5]
	v_mfma_f32_16x16x32_bf16 v[30:33], v[150:153], v[176:179], v[30:33]
	v_mfma_f32_16x16x32_bf16 v[26:29], v[158:161], v[176:179], v[26:29]
	v_mfma_f32_16x16x32_bf16 v[22:25], v[150:153], v[184:187], v[22:25]
	v_mfma_f32_16x16x32_bf16 v[18:21], v[158:161], v[184:187], v[18:21]
	v_mfma_f32_16x16x32_bf16 v[14:17], v[150:153], v[192:195], v[14:17]
	v_mfma_f32_16x16x32_bf16 v[10:13], v[158:161], v[192:195], v[10:13]
	v_mfma_f32_16x16x32_bf16 v[6:9], v[150:153], v[200:203], v[6:9]
	v_mfma_f32_16x16x32_bf16 v[2:5], v[158:161], v[200:203], v[2:5]
	s_setprio 0
	s_barrier
	s_add_i32 s68, s68, 2
	s_add_u32 s59, s59, 0x100
	s_addc_u32 s67, s67, 0
	s_add_u32 s0, s0, 0x100
	s_addc_u32 s1, s1, 0
	s_cmp_gt_u32 s68, 13
	s_cbranch_scc1 .Lpeel_exit_568

.Lpeel_exit_568:
	s_and_b64 vcc, exec, s[54:55]
	s_cbranch_vccz .LBB0_571
	s_barrier

.LBB0_659:
	s_ashr_i32 s53, s52, 31
	s_lshl_b64 s[34:35], s[52:53], 18
	s_add_u32 s54, s22, s34
	s_addc_u32 s55, s23, s35
	s_and_b64 s[34:35], s[2:3], exec
	s_cselect_b32 s34, s55, s63
	s_cselect_b32 s35, s54, s62
	s_ashr_i32 s51, s50, 31
	s_lshl_b64 s[56:57], s[50:51], 18
	v_readlane_b32 s51, v254, 37
	s_add_u32 s56, s51, s56
	v_readlane_b32 s51, v254, 38
	s_addc_u32 s57, s51, s57
	s_and_b64 s[78:79], s[2:3], exec
	s_cselect_b32 s51, s57, s61
	s_cselect_b32 s53, s56, s60
	s_add_u32 s78, s60, 0x100
	.p2align 8
	s_addc_u32 s79, s61, 0
	s_add_u32 s60, s62, 0x20080
	s_addc_u32 s61, s63, 0
	s_mov_b32 s62, -2
.Lpeel_660:
	ds_read_b128 v[98:101], v158
	ds_read_b128 v[102:105], v158 offset:1024
	ds_read_b128 v[106:109], v158 offset:2048
	ds_read_b128 v[110:113], v158 offset:3072
	ds_read_b128 v[162:165], v159
	ds_read_b128 v[166:169], v159 offset:1024
	ds_read_b128 v[170:173], v159 offset:2048
	ds_read_b128 v[174:177], v159 offset:3072
	s_add_u32 s63, s60, 0xfffe0080
	s_addc_u32 s80, s61, -1
	s_cmp_eq_u32 s62, 4
	s_cselect_b32 s81, s34, s80
	s_cselect_b32 s80, s35, s63
	s_cselect_b32 s83, s51, s79
	s_cselect_b32 s82, s53, s78
	v_lshl_add_u64 v[210:211], s[60:61], 0, v[152:153]
	s_add_i32 m0, s49, 0xc000
	ds_read_b128 v[178:181], v160
	ds_read_b128 v[182:185], v160 offset:1024
	ds_read_b128 v[186:189], v160 offset:2048
	ds_read_b128 v[190:193], v160 offset:3072
	ds_read_b128 v[194:197], v160 offset:4096
	ds_read_b128 v[198:201], v160 offset:5120
	ds_read_b128 v[202:205], v160 offset:6144
	ds_read_b128 v[206:209], v160 offset:7168
	global_load_lds_dwordx4 v[210:211], off
	v_lshl_add_u64 v[210:211], v[210:211], 0, s[4:5]
	s_add_i32 m0, s49, 0xe000
	s_nop 0
	global_load_lds_dwordx4 v[210:211], off
	s_waitcnt vmcnt(8)
	s_waitcnt lgkmcnt(0)
	s_barrier
	s_setprio 1
	s_waitcnt lgkmcnt(0)
	v_mfma_i32_16x16x64_i8 v[142:145], v[98:101], v[178:181], 0
	v_mfma_i32_16x16x64_i8 v[138:141], v[106:109], v[178:181], 0
	v_mfma_i32_16x16x64_i8 v[126:129], v[98:101], v[186:189], 0
	v_mfma_i32_16x16x64_i8 v[122:125], v[106:109], v[186:189], 0
	v_mfma_i32_16x16x64_i8 v[94:97], v[98:101], v[194:197], 0
	v_mfma_i32_16x16x64_i8 v[90:93], v[106:109], v[194:197], 0
	v_mfma_i32_16x16x64_i8 v[78:81], v[98:101], v[202:205], 0
	v_mfma_i32_16x16x64_i8 v[74:77], v[106:109], v[202:205], 0
	v_mfma_i32_16x16x64_i8 v[142:145], v[102:105], v[182:185], v[142:145]
	v_mfma_i32_16x16x64_i8 v[138:141], v[110:113], v[182:185], v[138:141]
	v_mfma_i32_16x16x64_i8 v[126:129], v[102:105], v[190:193], v[126:129]
	v_mfma_i32_16x16x64_i8 v[122:125], v[110:113], v[190:193], v[122:125]
	v_mfma_i32_16x16x64_i8 v[94:97], v[102:105], v[198:201], v[94:97]
	v_mfma_i32_16x16x64_i8 v[90:93], v[110:113], v[198:201], v[90:93]
	v_mfma_i32_16x16x64_i8 v[78:81], v[102:105], v[206:209], v[78:81]
	v_mfma_i32_16x16x64_i8 v[74:77], v[110:113], v[206:209], v[74:77]
	s_setprio 0
	s_setprio 1
	v_mfma_i32_16x16x64_i8 v[134:137], v[162:165], v[178:181], 0
	v_mfma_i32_16x16x64_i8 v[130:133], v[170:173], v[178:181], 0
	v_mfma_i32_16x16x64_i8 v[118:121], v[162:165], v[186:189], 0
	v_mfma_i32_16x16x64_i8 v[114:117], v[170:173], v[186:189], 0
	v_mfma_i32_16x16x64_i8 v[86:89], v[162:165], v[194:197], 0
	v_mfma_i32_16x16x64_i8 v[82:85], v[170:173], v[194:197], 0
	v_mfma_i32_16x16x64_i8 v[70:73], v[162:165], v[202:205], 0
	v_mfma_i32_16x16x64_i8 v[66:69], v[170:173], v[202:205], 0
	v_mfma_i32_16x16x64_i8 v[134:137], v[166:169], v[182:185], v[134:137]
	v_mfma_i32_16x16x64_i8 v[130:133], v[174:177], v[182:185], v[130:133]
	v_mfma_i32_16x16x64_i8 v[118:121], v[166:169], v[190:193], v[118:121]
	v_mfma_i32_16x16x64_i8 v[114:117], v[174:177], v[190:193], v[114:117]
	v_mfma_i32_16x16x64_i8 v[86:89], v[166:169], v[198:201], v[86:89]
	v_mfma_i32_16x16x64_i8 v[82:85], v[174:177], v[198:201], v[82:85]
	v_mfma_i32_16x16x64_i8 v[70:73], v[166:169], v[206:209], v[70:73]
	v_mfma_i32_16x16x64_i8 v[66:69], v[174:177], v[206:209], v[66:69]
	s_setprio 0
	s_barrier
	s_add_i32 s63, s72, s16
	v_lshl_add_u64 v[210:211], s[82:83], 0, v[148:149]
	s_mov_b32 m0, s63
	ds_read_b128 v[178:181], v160 offset:16384
	ds_read_b128 v[182:185], v160 offset:17408
	ds_read_b128 v[186:189], v160 offset:18432
	ds_read_b128 v[190:193], v160 offset:19456
	ds_read_b128 v[194:197], v160 offset:20480
	ds_read_b128 v[198:201], v160 offset:21504
	ds_read_b128 v[202:205], v160 offset:22528
	ds_read_b128 v[206:209], v160 offset:23552
	global_load_lds_dwordx4 v[210:211], off
	v_lshl_add_u64 v[212:213], v[210:211], 0, s[4:5]
	s_add_i32 m0, s63, 0x2000
	s_add_i32 s63, s73, s16
	global_load_lds_dwordx4 v[212:213], off
	v_lshl_add_u64 v[212:213], v[210:211], 0, s[8:9]
	s_mov_b32 m0, s63
	s_nop 0
	global_load_lds_dwordx4 v[212:213], off
	v_lshl_add_u64 v[212:213], v[210:211], 0, s[10:11]
	s_add_i32 m0, s63, 0x2000
	s_nop 0
	global_load_lds_dwordx4 v[212:213], off
	v_lshl_add_u64 v[212:213], s[80:81], 0, v[146:147]
	s_mov_b32 m0, s49
	v_lshl_add_u64 v[214:215], v[212:213], 0, s[4:5]
	global_load_lds_dwordx4 v[212:213], off
	s_mov_b32 m0, s64
	s_nop 0
	global_load_lds_dwordx4 v[214:215], off
	s_waitcnt vmcnt(8)
	s_waitcnt lgkmcnt(0)
	s_barrier
	s_setprio 1
	s_waitcnt lgkmcnt(0)
	v_mfma_i32_16x16x64_i8 v[62:65], v[98:101], v[178:181], 0
	v_mfma_i32_16x16x64_i8 v[58:61], v[106:109], v[178:181], 0
	v_mfma_i32_16x16x64_i8 v[46:49], v[98:101], v[186:189], 0
	v_mfma_i32_16x16x64_i8 v[42:45], v[106:109], v[186:189], 0
	v_mfma_i32_16x16x64_i8 v[30:33], v[98:101], v[194:197], 0
	v_mfma_i32_16x16x64_i8 v[26:29], v[106:109], v[194:197], 0
	v_mfma_i32_16x16x64_i8 v[14:17], v[98:101], v[202:205], 0
	v_mfma_i32_16x16x64_i8 v[10:13], v[106:109], v[202:205], 0
	v_mfma_i32_16x16x64_i8 v[62:65], v[102:105], v[182:185], v[62:65]
	v_mfma_i32_16x16x64_i8 v[58:61], v[110:113], v[182:185], v[58:61]
	v_mfma_i32_16x16x64_i8 v[46:49], v[102:105], v[190:193], v[46:49]
	v_mfma_i32_16x16x64_i8 v[42:45], v[110:113], v[190:193], v[42:45]
	v_mfma_i32_16x16x64_i8 v[30:33], v[102:105], v[198:201], v[30:33]
	v_mfma_i32_16x16x64_i8 v[26:29], v[110:113], v[198:201], v[26:29]
	v_mfma_i32_16x16x64_i8 v[14:17], v[102:105], v[206:209], v[14:17]
	v_mfma_i32_16x16x64_i8 v[10:13], v[110:113], v[206:209], v[10:13]
	s_setprio 0
	s_setprio 1
	v_mfma_i32_16x16x64_i8 v[54:57], v[162:165], v[178:181], 0
	v_mfma_i32_16x16x64_i8 v[50:53], v[170:173], v[178:181], 0
	v_mfma_i32_16x16x64_i8 v[38:41], v[162:165], v[186:189], 0
	v_mfma_i32_16x16x64_i8 v[34:37], v[170:173], v[186:189], 0
	v_mfma_i32_16x16x64_i8 v[22:25], v[162:165], v[194:197], 0
	v_mfma_i32_16x16x64_i8 v[18:21], v[170:173], v[194:197], 0
	v_mfma_i32_16x16x64_i8 v[6:9], v[162:165], v[202:205], 0
	v_mfma_i32_16x16x64_i8 v[2:5], v[170:173], v[202:205], 0
	v_mfma_i32_16x16x64_i8 v[54:57], v[166:169], v[182:185], v[54:57]
	v_mfma_i32_16x16x64_i8 v[50:53], v[174:177], v[182:185], v[50:53]
	v_mfma_i32_16x16x64_i8 v[38:41], v[166:169], v[190:193], v[38:41]
	v_mfma_i32_16x16x64_i8 v[34:37], v[174:177], v[190:193], v[34:37]
	v_mfma_i32_16x16x64_i8 v[22:25], v[166:169], v[198:201], v[22:25]
	v_mfma_i32_16x16x64_i8 v[18:21], v[174:177], v[198:201], v[18:21]
	v_mfma_i32_16x16x64_i8 v[6:9], v[166:169], v[206:209], v[6:9]
	v_mfma_i32_16x16x64_i8 v[2:5], v[174:177], v[206:209], v[2:5]
	s_setprio 0
	s_barrier
	s_add_i32 s63, 0, 0x18000
	s_add_i32 s80, 0, 0x1c000
	v_add_u32_e32 v110, s63, v1
	v_add_u32_e32 v150, s80, v1
	ds_read_b128 v[98:101], v110
	ds_read_b128 v[102:105], v110 offset:1024
	ds_read_b128 v[106:109], v110 offset:2048
	ds_read_b128 v[110:113], v110 offset:3072
	ds_read_b128 v[162:165], v150
	ds_read_b128 v[166:169], v150 offset:1024
	ds_read_b128 v[170:173], v150 offset:2048
	ds_read_b128 v[174:177], v150 offset:3072
	s_mov_b32 m0, s65
	v_lshl_add_u64 v[214:215], v[212:213], 0, s[8:9]
	ds_read_b128 v[178:181], v160 offset:32768
	ds_read_b128 v[182:185], v160 offset:33792
	ds_read_b128 v[186:189], v160 offset:34816
	ds_read_b128 v[190:193], v160 offset:35840
	ds_read_b128 v[194:197], v160 offset:36864
	ds_read_b128 v[198:201], v160 offset:37888
	ds_read_b128 v[202:205], v160 offset:38912
	ds_read_b128 v[206:209], v160 offset:39936
	global_load_lds_dwordx4 v[214:215], off
	v_lshl_add_u64 v[214:215], v[212:213], 0, s[10:11]
	s_mov_b32 m0, s66
	s_nop 0
	global_load_lds_dwordx4 v[214:215], off
	s_waitcnt vmcnt(8)
	s_waitcnt lgkmcnt(0)
	s_barrier
	s_setprio 1
	s_waitcnt lgkmcnt(0)
	v_mfma_i32_16x16x64_i8 v[142:145], v[98:101], v[178:181], v[142:145]
	v_mfma_i32_16x16x64_i8 v[138:141], v[106:109], v[178:181], v[138:141]
	v_mfma_i32_16x16x64_i8 v[126:129], v[98:101], v[186:189], v[126:129]
	v_mfma_i32_16x16x64_i8 v[122:125], v[106:109], v[186:189], v[122:125]
	v_mfma_i32_16x16x64_i8 v[94:97], v[98:101], v[194:197], v[94:97]
	v_mfma_i32_16x16x64_i8 v[90:93], v[106:109], v[194:197], v[90:93]
	v_mfma_i32_16x16x64_i8 v[78:81], v[98:101], v[202:205], v[78:81]
	v_mfma_i32_16x16x64_i8 v[74:77], v[106:109], v[202:205], v[74:77]
	v_mfma_i32_16x16x64_i8 v[142:145], v[102:105], v[182:185], v[142:145]
	v_mfma_i32_16x16x64_i8 v[138:141], v[110:113], v[182:185], v[138:141]
	v_mfma_i32_16x16x64_i8 v[126:129], v[102:105], v[190:193], v[126:129]
	v_mfma_i32_16x16x64_i8 v[122:125], v[110:113], v[190:193], v[122:125]
	v_mfma_i32_16x16x64_i8 v[94:97], v[102:105], v[198:201], v[94:97]
	v_mfma_i32_16x16x64_i8 v[90:93], v[110:113], v[198:201], v[90:93]
	v_mfma_i32_16x16x64_i8 v[78:81], v[102:105], v[206:209], v[78:81]
	v_mfma_i32_16x16x64_i8 v[74:77], v[110:113], v[206:209], v[74:77]
	s_setprio 0
	s_setprio 1
	v_mfma_i32_16x16x64_i8 v[134:137], v[162:165], v[178:181], v[134:137]
	v_mfma_i32_16x16x64_i8 v[130:133], v[170:173], v[178:181], v[130:133]
	v_mfma_i32_16x16x64_i8 v[118:121], v[162:165], v[186:189], v[118:121]
	v_mfma_i32_16x16x64_i8 v[114:117], v[170:173], v[186:189], v[114:117]
	v_mfma_i32_16x16x64_i8 v[86:89], v[162:165], v[194:197], v[86:89]
	v_mfma_i32_16x16x64_i8 v[82:85], v[170:173], v[194:197], v[82:85]
	v_mfma_i32_16x16x64_i8 v[70:73], v[162:165], v[202:205], v[70:73]
	v_mfma_i32_16x16x64_i8 v[66:69], v[170:173], v[202:205], v[66:69]
	v_mfma_i32_16x16x64_i8 v[134:137], v[166:169], v[182:185], v[134:137]
	v_mfma_i32_16x16x64_i8 v[130:133], v[174:177], v[182:185], v[130:133]
	v_mfma_i32_16x16x64_i8 v[118:121], v[166:169], v[190:193], v[118:121]
	v_mfma_i32_16x16x64_i8 v[114:117], v[174:177], v[190:193], v[114:117]
	v_mfma_i32_16x16x64_i8 v[86:89], v[166:169], v[198:201], v[86:89]
	v_mfma_i32_16x16x64_i8 v[82:85], v[174:177], v[198:201], v[82:85]
	v_mfma_i32_16x16x64_i8 v[70:73], v[166:169], v[206:209], v[70:73]
	v_mfma_i32_16x16x64_i8 v[66:69], v[174:177], v[206:209], v[66:69]
	s_setprio 0
	s_barrier
	s_add_i32 s63, s63, s16
	v_lshl_add_u64 v[214:215], v[210:211], 0, s[36:37]
	s_mov_b32 m0, s63
	ds_read_b128 v[178:181], v160 offset:49152
	ds_read_b128 v[182:185], v160 offset:50176
	ds_read_b128 v[186:189], v160 offset:51200
	ds_read_b128 v[190:193], v160 offset:52224
	ds_read_b128 v[194:197], v160 offset:53248
	ds_read_b128 v[198:201], v160 offset:54272
	ds_read_b128 v[202:205], v160 offset:55296
	ds_read_b128 v[206:209], v160 offset:56320
	global_load_lds_dwordx4 v[214:215], off
	v_lshl_add_u64 v[214:215], v[210:211], 0, s[40:41]
	s_add_i32 m0, s63, 0x2000
	s_add_i32 s63, s80, s16
	global_load_lds_dwordx4 v[214:215], off
	v_lshl_add_u64 v[214:215], v[210:211], 0, s[42:43]
	s_mov_b32 m0, s63
	v_lshl_add_u64 v[210:211], v[210:211], 0, s[44:45]
	global_load_lds_dwordx4 v[214:215], off
	s_add_i32 m0, s63, 0x2000
	s_nop 0
	global_load_lds_dwordx4 v[210:211], off
	v_lshl_add_u64 v[210:211], v[212:213], 0, s[36:37]
	s_mov_b32 m0, s68
	s_nop 0
	global_load_lds_dwordx4 v[210:211], off
	v_lshl_add_u64 v[210:211], v[212:213], 0, s[40:41]
	s_mov_b32 m0, s69
	s_nop 0
	global_load_lds_dwordx4 v[210:211], off
	s_waitcnt vmcnt(8)
	s_waitcnt lgkmcnt(0)
	s_barrier
	s_setprio 1
	s_waitcnt lgkmcnt(0)
	v_mfma_i32_16x16x64_i8 v[62:65], v[98:101], v[178:181], v[62:65]
	v_mfma_i32_16x16x64_i8 v[58:61], v[106:109], v[178:181], v[58:61]
	v_mfma_i32_16x16x64_i8 v[46:49], v[98:101], v[186:189], v[46:49]
	v_mfma_i32_16x16x64_i8 v[42:45], v[106:109], v[186:189], v[42:45]
	v_mfma_i32_16x16x64_i8 v[30:33], v[98:101], v[194:197], v[30:33]
	v_mfma_i32_16x16x64_i8 v[26:29], v[106:109], v[194:197], v[26:29]
	v_mfma_i32_16x16x64_i8 v[14:17], v[98:101], v[202:205], v[14:17]
	v_mfma_i32_16x16x64_i8 v[10:13], v[106:109], v[202:205], v[10:13]
	v_mfma_i32_16x16x64_i8 v[62:65], v[102:105], v[182:185], v[62:65]
	v_mfma_i32_16x16x64_i8 v[58:61], v[110:113], v[182:185], v[58:61]
	v_mfma_i32_16x16x64_i8 v[46:49], v[102:105], v[190:193], v[46:49]
	v_mfma_i32_16x16x64_i8 v[42:45], v[110:113], v[190:193], v[42:45]
	v_mfma_i32_16x16x64_i8 v[30:33], v[102:105], v[198:201], v[30:33]
	v_mfma_i32_16x16x64_i8 v[26:29], v[110:113], v[198:201], v[26:29]
	v_mfma_i32_16x16x64_i8 v[14:17], v[102:105], v[206:209], v[14:17]
	v_mfma_i32_16x16x64_i8 v[10:13], v[110:113], v[206:209], v[10:13]
	s_setprio 0
	s_setprio 1
	v_mfma_i32_16x16x64_i8 v[54:57], v[162:165], v[178:181], v[54:57]
	v_mfma_i32_16x16x64_i8 v[50:53], v[170:173], v[178:181], v[50:53]
	v_mfma_i32_16x16x64_i8 v[38:41], v[162:165], v[186:189], v[38:41]
	v_mfma_i32_16x16x64_i8 v[34:37], v[170:173], v[186:189], v[34:37]
	v_mfma_i32_16x16x64_i8 v[22:25], v[162:165], v[194:197], v[22:25]
	v_mfma_i32_16x16x64_i8 v[18:21], v[170:173], v[194:197], v[18:21]
	v_mfma_i32_16x16x64_i8 v[6:9], v[162:165], v[202:205], v[6:9]
	v_mfma_i32_16x16x64_i8 v[2:5], v[170:173], v[202:205], v[2:5]
	v_mfma_i32_16x16x64_i8 v[54:57], v[166:169], v[182:185], v[54:57]
	v_mfma_i32_16x16x64_i8 v[50:53], v[174:177], v[182:185], v[50:53]
	v_mfma_i32_16x16x64_i8 v[38:41], v[166:169], v[190:193], v[38:41]
	v_mfma_i32_16x16x64_i8 v[34:37], v[174:177], v[190:193], v[34:37]
	v_mfma_i32_16x16x64_i8 v[22:25], v[166:169], v[198:201], v[22:25]
	v_mfma_i32_16x16x64_i8 v[18:21], v[174:177], v[198:201], v[18:21]
	v_mfma_i32_16x16x64_i8 v[6:9], v[166:169], v[206:209], v[6:9]
	v_mfma_i32_16x16x64_i8 v[2:5], v[174:177], v[206:209], v[2:5]
	s_setprio 0
	s_barrier
	s_add_i32 s62, s62, 2
	s_add_u32 s78, s78, 0x100
	s_addc_u32 s79, s79, 0
	s_add_u32 s60, s60, 0x100
	s_addc_u32 s61, s61, 0
	s_cmp_gt_u32 s62, 5
	s_cbranch_scc1 .Lpeel_exit_660

.Lpeel_exit_660:
	s_and_b64 vcc, exec, s[46:47]
	s_cbranch_vccz .LBB0_663
	s_barrier

.LBB0_720:
	s_add_u32 s35, s6, 0x100
	.p2align 8
	s_addc_u32 s66, s7, 0
	s_add_u32 s0, s64, 0x58080
	s_addc_u32 s1, s65, 0
	s_mov_b32 s67, -2
.Lpeel_721:
	ds_read_b128 v[128:131], v217
	ds_read_b128 v[132:135], v217 offset:1024
	ds_read_b128 v[136:139], v217 offset:2048
	ds_read_b128 v[140:143], v217 offset:3072
	ds_read_b128 v[144:147], v218
	ds_read_b128 v[148:151], v218 offset:1024
	ds_read_b128 v[152:155], v218 offset:2048
	ds_read_b128 v[156:159], v218 offset:3072
	s_add_u32 s6, s0, 0xfffa8080
	s_addc_u32 s7, s1, -1
	s_cmp_eq_u32 s67, 18
	s_cselect_b32 s7, s61, s7
	s_cselect_b32 s6, s60, s6
	s_cselect_b32 s65, s63, s66
	s_cselect_b32 s64, s62, s35
	v_lshl_add_u64 v[192:193], s[0:1], 0, v[190:191]
	s_add_i32 m0, s17, 0xc000
	ds_read_b128 v[160:163], v219
	ds_read_b128 v[164:167], v219 offset:1024
	ds_read_b128 v[168:171], v219 offset:2048
	ds_read_b128 v[172:175], v219 offset:3072
	ds_read_b128 v[176:179], v219 offset:4096
	ds_read_b128 v[180:183], v219 offset:5120
	ds_read_b128 v[196:199], v219 offset:6144
	ds_read_b128 v[200:203], v219 offset:7168
	global_load_lds_dwordx4 v[192:193], off
	v_lshl_add_u64 v[192:193], v[192:193], 0, s[8:9]
	s_add_i32 m0, s17, 0xe000
	s_nop 0
	global_load_lds_dwordx4 v[192:193], off
	s_waitcnt vmcnt(8)
	s_waitcnt lgkmcnt(0)
	s_barrier
	s_setprio 1
	s_waitcnt lgkmcnt(0)
	v_mfma_scale_f32_16x16x128_f8f6f4 v[124:127], v[128:135], v[160:167], 0, v220, v220 op_sel_hi:[0, 0, 0]
	v_mfma_scale_f32_16x16x128_f8f6f4 v[120:123], v[136:143], v[160:167], 0, v220, v220 op_sel_hi:[0, 0, 0]
	v_mfma_scale_f32_16x16x128_f8f6f4 v[108:111], v[128:135], v[168:175], 0, v220, v220 op_sel_hi:[0, 0, 0]
	v_mfma_scale_f32_16x16x128_f8f6f4 v[104:107], v[136:143], v[168:175], 0, v220, v220 op_sel_hi:[0, 0, 0]
	v_mfma_scale_f32_16x16x128_f8f6f4 v[204:207], v[128:135], v[176:183], 0, v220, v220 op_sel_hi:[0, 0, 0]
	v_mfma_scale_f32_16x16x128_f8f6f4 v[208:211], v[136:143], v[176:183], 0, v220, v220 op_sel_hi:[0, 0, 0]
	v_mfma_scale_f32_16x16x128_f8f6f4 v[212:215], v[128:135], v[196:203], 0, v220, v220 op_sel_hi:[0, 0, 0]
	v_mfma_scale_f32_16x16x128_f8f6f4 v[222:225], v[136:143], v[196:203], 0, v220, v220 op_sel_hi:[0, 0, 0]
	s_setprio 0
	s_setprio 1
	v_mfma_scale_f32_16x16x128_f8f6f4 v[116:119], v[144:151], v[160:167], 0, v220, v220 op_sel_hi:[0, 0, 0]
	v_mfma_scale_f32_16x16x128_f8f6f4 v[112:115], v[152:159], v[160:167], 0, v220, v220 op_sel_hi:[0, 0, 0]
	v_mfma_scale_f32_16x16x128_f8f6f4 v[100:103], v[144:151], v[168:175], 0, v220, v220 op_sel_hi:[0, 0, 0]
	v_mfma_scale_f32_16x16x128_f8f6f4 v[96:99], v[152:159], v[168:175], 0, v220, v220 op_sel_hi:[0, 0, 0]
	v_mfma_scale_f32_16x16x128_f8f6f4 v[160:163], v[144:151], v[176:183], 0, v220, v220 op_sel_hi:[0, 0, 0]
	v_mfma_scale_f32_16x16x128_f8f6f4 v[164:167], v[152:159], v[176:183], 0, v220, v220 op_sel_hi:[0, 0, 0]
	v_mfma_scale_f32_16x16x128_f8f6f4 v[168:171], v[144:151], v[196:203], 0, v220, v220 op_sel_hi:[0, 0, 0]
	v_mfma_scale_f32_16x16x128_f8f6f4 v[172:175], v[152:159], v[196:203], 0, v220, v220 op_sel_hi:[0, 0, 0]
	s_setprio 0
	s_barrier
	v_lshl_add_u64 v[184:185], s[64:65], 0, v[188:189]
	s_add_i32 s64, s84, s16
	s_mov_b32 m0, s64
	ds_read_b128 v[64:67], v219 offset:16384
	ds_read_b128 v[68:71], v219 offset:17408
	ds_read_b128 v[72:75], v219 offset:18432
	ds_read_b128 v[76:79], v219 offset:19456
	ds_read_b128 v[80:83], v219 offset:20480
	ds_read_b128 v[84:87], v219 offset:21504
	ds_read_b128 v[88:91], v219 offset:22528
	ds_read_b128 v[92:95], v219 offset:23552
	global_load_lds_dwordx4 v[184:185], off
	v_lshl_add_u64 v[176:177], v[184:185], 0, s[8:9]
	s_add_i32 m0, s64, 0x2000
	s_add_i32 s64, s85, s16
	global_load_lds_dwordx4 v[176:177], off
	v_lshl_add_u64 v[176:177], v[184:185], 0, s[10:11]
	s_mov_b32 m0, s64
	v_lshl_add_u64 v[186:187], s[6:7], 0, v[238:239]
	global_load_lds_dwordx4 v[176:177], off
	v_lshl_add_u64 v[176:177], v[184:185], 0, s[12:13]
	s_add_i32 m0, s64, 0x2000
	s_nop 0
	global_load_lds_dwordx4 v[176:177], off
	s_mov_b32 m0, s17
	v_lshl_add_u64 v[176:177], v[186:187], 0, s[8:9]
	global_load_lds_dwordx4 v[186:187], off
	s_mov_b32 m0, s33
	s_nop 0
	global_load_lds_dwordx4 v[176:177], off
	s_waitcnt vmcnt(8)
	s_waitcnt lgkmcnt(0)
	s_barrier
	s_setprio 1
	s_waitcnt lgkmcnt(0)
	v_mfma_scale_f32_16x16x128_f8f6f4 v[60:63], v[128:135], v[64:71], 0, v220, v220 op_sel_hi:[0, 0, 0]
	v_mfma_scale_f32_16x16x128_f8f6f4 v[56:59], v[136:143], v[64:71], 0, v220, v220 op_sel_hi:[0, 0, 0]
	v_mfma_scale_f32_16x16x128_f8f6f4 v[226:229], v[128:135], v[88:95], 0, v220, v220 op_sel_hi:[0, 0, 0]
	v_mfma_scale_f32_16x16x128_f8f6f4 v[230:233], v[136:143], v[88:95], 0, v220, v220 op_sel_hi:[0, 0, 0]
	v_mfma_scale_f32_16x16x128_f8f6f4 v[176:179], v[128:135], v[72:79], 0, v220, v220 op_sel_hi:[0, 0, 0]
	v_mfma_scale_f32_16x16x128_f8f6f4 v[180:183], v[136:143], v[72:79], 0, v220, v220 op_sel_hi:[0, 0, 0]
	v_mfma_scale_f32_16x16x128_f8f6f4 v[196:199], v[128:135], v[80:87], 0, v220, v220 op_sel_hi:[0, 0, 0]
	v_mfma_scale_f32_16x16x128_f8f6f4 v[200:203], v[136:143], v[80:87], 0, v220, v220 op_sel_hi:[0, 0, 0]
	s_setprio 0
	s_setprio 1
	v_mfma_scale_f32_16x16x128_f8f6f4 v[52:55], v[144:151], v[64:71], 0, v220, v220 op_sel_hi:[0, 0, 0]
	v_mfma_scale_f32_16x16x128_f8f6f4 v[48:51], v[152:159], v[64:71], 0, v220, v220 op_sel_hi:[0, 0, 0]
	v_mfma_scale_f32_16x16x128_f8f6f4 v[242:245], v[144:151], v[80:87], 0, v220, v220 op_sel_hi:[0, 0, 0]
	v_mfma_scale_f32_16x16x128_f8f6f4 v[234:237], v[144:151], v[72:79], 0, v220, v220 op_sel_hi:[0, 0, 0]
	v_mfma_scale_f32_16x16x128_f8f6f4 v[66:69], v[152:159], v[72:79], 0, v220, v220 op_sel_hi:[0, 0, 0]
	v_mfma_scale_f32_16x16x128_f8f6f4 v[246:249], v[152:159], v[80:87], 0, v220, v220 op_sel_hi:[0, 0, 0]
	v_mfma_scale_f32_16x16x128_f8f6f4 v[250:253], v[144:151], v[88:95], 0, v220, v220 op_sel_hi:[0, 0, 0]
	v_mfma_scale_f32_16x16x128_f8f6f4 v[192:195], v[152:159], v[88:95], 0, v220, v220 op_sel_hi:[0, 0, 0]
	s_setprio 0
	s_barrier
	s_add_i32 s6, 0, 0x18000
	v_add_u32_e32 v8, s6, v216
	s_add_i32 s7, 0, 0x1c000
	s_nop 1
	ds_read_b128 v[0:3], v8
	ds_read_b128 v[4:7], v8 offset:1024
	ds_read_b128 v[16:19], v8 offset:2048
	ds_read_b128 v[20:23], v8 offset:3072
	v_add_u32_e32 v8, s7, v216
	ds_read_b128 v[128:131], v8
	ds_read_b128 v[132:135], v8 offset:1024
	ds_read_b128 v[136:139], v8 offset:2048
	ds_read_b128 v[140:143], v8 offset:3072
	s_mov_b32 m0, s47
	v_lshl_add_u64 v[64:65], v[186:187], 0, s[10:11]
	ds_read_b128 v[8:11], v219 offset:32768
	ds_read_b128 v[12:15], v219 offset:33792
	ds_read_b128 v[24:27], v219 offset:34816
	ds_read_b128 v[28:31], v219 offset:35840
	ds_read_b128 v[32:35], v219 offset:36864
	ds_read_b128 v[36:39], v219 offset:37888
	ds_read_b128 v[40:43], v219 offset:38912
	ds_read_b128 v[44:47], v219 offset:39936
	global_load_lds_dwordx4 v[64:65], off
	v_lshl_add_u64 v[64:65], v[186:187], 0, s[12:13]
	s_mov_b32 m0, s57
	s_nop 0
	global_load_lds_dwordx4 v[64:65], off
	s_waitcnt vmcnt(8)
	s_waitcnt lgkmcnt(0)
	s_barrier
	s_setprio 1
	s_waitcnt lgkmcnt(0)
	v_mfma_scale_f32_16x16x128_f8f6f4 v[124:127], v[0:7], v[8:15], v[124:127], v220, v220 op_sel_hi:[0,0,0]
	v_mfma_scale_f32_16x16x128_f8f6f4 v[120:123], v[16:23], v[8:15], v[120:123], v220, v220 op_sel_hi:[0,0,0]
	v_mfma_scale_f32_16x16x128_f8f6f4 v[108:111], v[0:7], v[24:31], v[108:111], v220, v220 op_sel_hi:[0,0,0]
	v_mfma_scale_f32_16x16x128_f8f6f4 v[104:107], v[16:23], v[24:31], v[104:107], v220, v220 op_sel_hi:[0,0,0]
	v_mfma_scale_f32_16x16x128_f8f6f4 v[92:95], v[0:7], v[32:39], v[204:207], v220, v220 op_sel_hi:[0,0,0]
	v_mfma_scale_f32_16x16x128_f8f6f4 v[88:91], v[16:23], v[32:39], v[208:211], v220, v220 op_sel_hi:[0,0,0]
	v_mfma_scale_f32_16x16x128_f8f6f4 v[76:79], v[0:7], v[40:47], v[212:215], v220, v220 op_sel_hi:[0,0,0]
	v_mfma_scale_f32_16x16x128_f8f6f4 v[72:75], v[16:23], v[40:47], v[222:225], v220, v220 op_sel_hi:[0,0,0]
	s_setprio 0
	s_setprio 1
	v_mfma_scale_f32_16x16x128_f8f6f4 v[116:119], v[128:135], v[8:15], v[116:119], v220, v220 op_sel_hi:[0,0,0]
	v_mfma_scale_f32_16x16x128_f8f6f4 v[112:115], v[136:143], v[8:15], v[112:115], v220, v220 op_sel_hi:[0,0,0]
	v_mfma_scale_f32_16x16x128_f8f6f4 v[100:103], v[128:135], v[24:31], v[100:103], v220, v220 op_sel_hi:[0,0,0]
	v_mfma_scale_f32_16x16x128_f8f6f4 v[96:99], v[136:143], v[24:31], v[96:99], v220, v220 op_sel_hi:[0,0,0]
	v_mfma_scale_f32_16x16x128_f8f6f4 v[84:87], v[128:135], v[32:39], v[160:163], v220, v220 op_sel_hi:[0,0,0]
	v_mfma_scale_f32_16x16x128_f8f6f4 v[80:83], v[136:143], v[32:39], v[164:167], v220, v220 op_sel_hi:[0,0,0]
	v_mfma_scale_f32_16x16x128_f8f6f4 v[24:27], v[128:135], v[40:47], v[168:171], v220, v220 op_sel_hi:[0,0,0]
	v_mfma_scale_f32_16x16x128_f8f6f4 v[10:13], v[136:143], v[40:47], v[172:175], v220, v220 op_sel_hi:[0,0,0]
	s_setprio 0
	s_barrier
	s_add_i32 s6, s6, s16
	v_lshl_add_u64 v[8:9], v[184:185], 0, s[28:29]
	s_mov_b32 m0, s6
	ds_read_b128 v[32:35], v219 offset:49152
	ds_read_b128 v[36:39], v219 offset:50176
	ds_read_b128 v[144:147], v219 offset:51200
	ds_read_b128 v[148:151], v219 offset:52224
	ds_read_b128 v[152:155], v219 offset:53248
	ds_read_b128 v[156:159], v219 offset:54272
	ds_read_b128 v[160:163], v219 offset:55296
	ds_read_b128 v[164:167], v219 offset:56320
	global_load_lds_dwordx4 v[8:9], off
	v_lshl_add_u64 v[8:9], v[184:185], 0, s[36:37]
	s_add_i32 m0, s6, 0x2000
	s_add_i32 s6, s7, s16
	global_load_lds_dwordx4 v[8:9], off
	v_lshl_add_u64 v[8:9], v[184:185], 0, s[40:41]
	s_mov_b32 m0, s6
	s_nop 0
	global_load_lds_dwordx4 v[8:9], off
	v_lshl_add_u64 v[8:9], v[184:185], 0, s[42:43]
	s_add_i32 m0, s6, 0x2000
	s_nop 0
	global_load_lds_dwordx4 v[8:9], off
	v_lshl_add_u64 v[8:9], v[186:187], 0, s[28:29]
	s_mov_b32 m0, s77
	s_nop 0
	global_load_lds_dwordx4 v[8:9], off
	v_lshl_add_u64 v[8:9], v[186:187], 0, s[36:37]
	s_mov_b32 m0, s78
	s_nop 0
	global_load_lds_dwordx4 v[8:9], off
	s_waitcnt vmcnt(8)
	s_waitcnt lgkmcnt(0)
	s_barrier
	s_setprio 1
	s_waitcnt lgkmcnt(0)
	v_mfma_scale_f32_16x16x128_f8f6f4 v[60:63], v[0:7], v[32:39], v[60:63], v220, v220 op_sel_hi:[0,0,0]
	v_mfma_scale_f32_16x16x128_f8f6f4 v[56:59], v[16:23], v[32:39], v[56:59], v220, v220 op_sel_hi:[0,0,0]
	v_mfma_scale_f32_16x16x128_f8f6f4 v[44:47], v[0:7], v[144:151], v[176:179], v220, v220 op_sel_hi:[0,0,0]
	v_mfma_scale_f32_16x16x128_f8f6f4 v[40:43], v[16:23], v[144:151], v[180:183], v220, v220 op_sel_hi:[0,0,0]
	v_mfma_scale_f32_16x16x128_f8f6f4 v[28:31], v[0:7], v[152:159], v[196:199], v220, v220 op_sel_hi:[0,0,0]
	v_mfma_scale_f32_16x16x128_f8f6f4 v[226:229], v[0:7], v[160:167], v[226:229], v220, v220 op_sel_hi:[0,0,0]
	v_mfma_scale_f32_16x16x128_f8f6f4 v[230:233], v[16:23], v[160:167], v[230:233], v220, v220 op_sel_hi:[0,0,0]
	v_mfma_scale_f32_16x16x128_f8f6f4 v[168:171], v[16:23], v[152:159], v[200:203], v220, v220 op_sel_hi:[0,0,0]
	s_setprio 0
	s_setprio 1
	v_mfma_scale_f32_16x16x128_f8f6f4 v[52:55], v[128:135], v[32:39], v[52:55], v220, v220 op_sel_hi:[0,0,0]
	v_mfma_scale_f32_16x16x128_f8f6f4 v[48:51], v[136:143], v[32:39], v[48:51], v220, v220 op_sel_hi:[0,0,0]
	v_mfma_scale_f32_16x16x128_f8f6f4 v[36:39], v[128:135], v[144:151], v[234:237], v220, v220 op_sel_hi:[0,0,0]
	v_mfma_scale_f32_16x16x128_f8f6f4 v[32:35], v[136:143], v[144:151], v[66:69], v220, v220 op_sel_hi:[0,0,0]
	v_mfma_scale_f32_16x16x128_f8f6f4 v[20:23], v[128:135], v[152:159], v[242:245], v220, v220 op_sel_hi:[0,0,0]
	v_mfma_scale_f32_16x16x128_f8f6f4 v[16:19], v[136:143], v[152:159], v[246:249], v220, v220 op_sel_hi:[0,0,0]
	s_nop 5
	v_mov_b64_e32 v[244:245], v[170:171]
	v_mov_b64_e32 v[242:243], v[168:169]
	v_mfma_scale_f32_16x16x128_f8f6f4 v[4:7], v[128:135], v[160:167], v[250:253], v220, v220 op_sel_hi:[0,0,0]
	v_mfma_scale_f32_16x16x128_f8f6f4 v[0:3], v[136:143], v[160:167], v[192:195], v220, v220 op_sel_hi:[0,0,0]
	s_setprio 0
	s_barrier
	s_add_i32 s67, s67, 2
	s_add_u32 s35, s35, 0x100
	s_addc_u32 s66, s66, 0
	s_add_u32 s0, s0, 0x100
	s_addc_u32 s1, s1, 0
	s_cmp_gt_u32 s67, 19
	s_cbranch_scc1 .Lpeel_exit_721

.Lpeel_exit_721:
	s_and_b64 vcc, exec, s[44:45]
	s_cbranch_vccz .LBB0_724
	s_barrier
